# v096 variant: the retention workgroups run their 3 early GEMV units in one call through the GEMV unit loop (conditioning vectors staged once)
# baseline (speedup 1.0000x reference)
.LBB0_16:
	s_or_b64 exec, exec, s[46:47]
	v_readlane_b32 s0, v254, 31
	s_add_i32 s56, s56, s3
	s_add_i32 s48, s48, s0
	s_cmp_eq_u32 s100, 3
	s_cbranch_scc0 .Lmy_g_st
	s_sub_i32 s56, s56, s3
	s_add_i32 s56, s56, 64
	s_sub_i32 s48, s48, s0
	s_addk_i32 s48, 0x1000
.Lmy_g_st:
	s_cmpk_gt_i32 s56, 0xbf
	s_mov_b64 s[46:47], -1
	s_barrier
	s_cbranch_scc1 .LBB0_37

.Lpb_next:
	s_add_i32 s65, s65, s3
	s_cmpk_lt_i32 s65, 0x440
	s_cbranch_scc1 .Lpb_loop
	s_branch .LBB0_178
	s_nop 0
	s_nop 0
	s_nop 0
	s_nop 0
	s_nop 0
	s_nop 0
	s_nop 0
	s_nop 0
	s_nop 0
	s_nop 0
	s_nop 0
	s_nop 0
	s_nop 0
	s_nop 0
	s_nop 0
	s_nop 0
	s_nop 0
	s_nop 0
	s_nop 0
	s_nop 0
	s_nop 0
	s_branch .LBB0_178
	s_nop 0
	s_nop 0
	s_nop 0
	s_nop 0
	s_nop 0
	s_nop 0
	s_nop 0
	s_nop 0
	s_nop 0
	s_nop 0
	s_nop 0
	s_nop 0
	s_nop 0
.LBB0_178:
	v_readlane_b32 s0, v255, 10
	v_readlane_b32 s60, v255, 0
	s_add_i32 s0, s0, 2
	v_readlane_b32 s63, v255, 3
	v_readlane_b32 s62, v255, 2
	s_cmp_ge_i32 s0, s63
	s_barrier
	v_readlane_b32 s61, v255, 1
	s_cbranch_scc1 .LBB0_190
	s_waitcnt vmcnt(0)
	s_barrier
	s_mov_b64 s[4:5], exec
	v_readlane_b32 s6, v254, 56
	v_readlane_b32 s7, v254, 57
	v_readlane_b32 s60, v255, 6
	s_and_b64 s[6:7], s[4:5], s[6:7]
	v_readlane_b32 s61, v255, 7
	s_mov_b64 exec, s[6:7]
	s_cbranch_execz .LBB0_228
	v_readlane_b32 s2, v253, 2
	s_waitcnt vmcnt(0) expcnt(0) lgkmcnt(0)
	s_nop 0
	v_mov_b32_e32 v2, s2
	ds_read_b32 v4, v2
	ds_read_b32 v2, v2 offset:4
	s_waitcnt lgkmcnt(1)
	v_cmp_ne_u32_e32 vcc, 0, v4
	s_cbranch_vccnz .LBB0_196
	v_readlane_b32 s8, v253, 0
	v_readlane_b32 s9, v253, 1
	s_load_dwordx2 s[6:7], s[8:9], 0x4
	s_mov_b32 s12, 1
	s_waitcnt lgkmcnt(0)
	s_mul_i32 s2, s6, s3
	s_mul_i32 s2, s2, s7
	s_branch .LBB0_183

.LBB0_566:
	v_readlane_b32 s0, v255, 8
	s_nop 3
	s_cmp_lg_u32 s0, 0
	s_cbranch_scc1 .Lmy_d_nocall
	s_cmpk_lg_i32 s3, 0x100
	s_cbranch_scc1 .Lmy_d_nocall
	s_cmpk_lt_i32 s76, 0x80
	s_cbranch_scc1 .Lmy_d_nocall
	s_cmpk_gt_i32 s76, 0xbf
	s_cbranch_scc1 .Lmy_d_nocall
	s_mov_b32 s100, 3
	s_mov_b32 s0, 1
	v_writelane_b32 v255, s0, 8
	s_add_i32 s101, s76, 0xffffff80
	s_waitcnt vmcnt(0) lgkmcnt(0)
	s_barrier
	s_branch .Lmy_tr_acall
.Lmy_d_ret:
	s_mov_b32 s100, 0
	s_mov_b32 s0, 0
	v_writelane_b32 v255, s0, 8
	s_nop 1

.LBB0_695:
	v_lshl_add_u32 v148, s6, 8, v150
	s_lshl_b32 s0, s4, 8
	v_or_b32_e32 v149, s0, v152
	v_mov_b32_e32 v181, 0
	v_lshlrev_b32_e32 v180, 11, v148
	v_lshl_add_u32 v180, v149, 1, v180
	v_lshl_add_u64 v[142:143], s[40:41], 0, v[180:181]
	v_lshlrev_b32_e32 v180, 2, v149
	v_lshl_add_u64 v[178:179], s[46:47], 0, v[180:181]
	global_load_dwordx4 v[154:157], v[178:179], off
	global_load_dwordx4 v[158:161], v[178:179], off offset:16
	global_load_dwordx4 v[162:165], v[178:179], off offset:512
	global_load_dwordx4 v[166:169], v[178:179], off offset:528
	s_add_i32 s4, s0, 0x2400
	s_ashr_i32 s0, s4, 9
	s_mul_hi_i32 s4, s0, 0x1100000
	s_mul_i32 s0, s0, 0x1100000
	s_add_u32 s58, s65, s0
	s_addc_u32 s59, s66, s4
	v_and_b32_e32 v180, 0x1ff, v149
	v_lshlrev_b32_e32 v180, 1, v180
	v_lshl_add_u32 v180, v148, 10, v180
	v_lshl_add_u64 v[144:145], s[58:59], 0, v[180:181]
	v_lshlrev_b32_e32 v180, 13, v148
	v_lshl_add_u32 v180, v149, 1, v180
	v_add_u32_e32 v180, 0x1000, v180
	v_lshl_add_u64 v[146:147], s[44:45], 0, v[180:181]
	global_load_dwordx4 v[170:173], v[142:143], off
	global_load_dwordx4 v[174:177], v[144:145], off
	s_waitcnt vmcnt(2)
	v_pk_add_f32 v[126:127], v[126:127], v[154:155]
	v_pk_add_f32 v[122:123], v[122:123], v[158:159]
	v_pk_add_f32 v[128:129], v[128:129], v[156:157]
	v_pk_add_f32 v[124:125], v[124:125], v[160:161]
	v_pk_add_f32 v[118:119], v[118:119], v[162:163]
	v_pk_add_f32 v[114:115], v[114:115], v[166:167]
	v_pk_add_f32 v[120:121], v[120:121], v[164:165]
	v_pk_add_f32 v[116:117], v[116:117], v[168:169]
	v_pk_add_f32 v[110:111], v[110:111], v[154:155]
	v_pk_add_f32 v[106:107], v[106:107], v[158:159]
	v_pk_add_f32 v[112:113], v[112:113], v[156:157]
	v_pk_add_f32 v[108:109], v[108:109], v[160:161]
	v_pk_add_f32 v[102:103], v[102:103], v[162:163]
	v_pk_add_f32 v[98:99], v[98:99], v[166:167]
	v_pk_add_f32 v[104:105], v[104:105], v[164:165]
	v_pk_add_f32 v[100:101], v[100:101], v[168:169]
	v_pk_add_f32 v[94:95], v[94:95], v[154:155]
	v_pk_add_f32 v[90:91], v[90:91], v[158:159]
	v_pk_add_f32 v[96:97], v[96:97], v[156:157]
	v_pk_add_f32 v[92:93], v[92:93], v[160:161]
	v_pk_add_f32 v[86:87], v[86:87], v[162:163]
	v_pk_add_f32 v[82:83], v[82:83], v[166:167]
	v_pk_add_f32 v[88:89], v[88:89], v[164:165]
	v_pk_add_f32 v[84:85], v[84:85], v[168:169]
	v_pk_add_f32 v[78:79], v[78:79], v[154:155]
	v_pk_add_f32 v[74:75], v[74:75], v[158:159]
	v_pk_add_f32 v[80:81], v[80:81], v[156:157]
	v_pk_add_f32 v[76:77], v[76:77], v[160:161]
	v_pk_add_f32 v[70:71], v[70:71], v[162:163]
	v_pk_add_f32 v[66:67], v[66:67], v[166:167]
	v_pk_add_f32 v[72:73], v[72:73], v[164:165]
	v_pk_add_f32 v[68:69], v[68:69], v[168:169]
	v_pk_add_f32 v[62:63], v[62:63], v[154:155]
	v_pk_add_f32 v[58:59], v[58:59], v[158:159]
	v_pk_add_f32 v[64:65], v[64:65], v[156:157]
	v_pk_add_f32 v[60:61], v[60:61], v[160:161]
	v_pk_add_f32 v[54:55], v[54:55], v[162:163]
	v_pk_add_f32 v[50:51], v[50:51], v[166:167]
	v_pk_add_f32 v[56:57], v[56:57], v[164:165]
	v_pk_add_f32 v[52:53], v[52:53], v[168:169]
	v_pk_add_f32 v[46:47], v[46:47], v[154:155]
	v_pk_add_f32 v[42:43], v[42:43], v[158:159]
	v_pk_add_f32 v[48:49], v[48:49], v[156:157]
	v_pk_add_f32 v[44:45], v[44:45], v[160:161]
	v_pk_add_f32 v[38:39], v[38:39], v[162:163]
	v_pk_add_f32 v[34:35], v[34:35], v[166:167]
	v_pk_add_f32 v[40:41], v[40:41], v[164:165]
	v_pk_add_f32 v[36:37], v[36:37], v[168:169]
	v_pk_add_f32 v[30:31], v[30:31], v[154:155]
	v_pk_add_f32 v[26:27], v[26:27], v[158:159]
	v_pk_add_f32 v[32:33], v[32:33], v[156:157]
	v_pk_add_f32 v[28:29], v[28:29], v[160:161]
	v_pk_add_f32 v[22:23], v[22:23], v[162:163]
	v_pk_add_f32 v[18:19], v[18:19], v[166:167]
	v_pk_add_f32 v[24:25], v[24:25], v[164:165]
	v_pk_add_f32 v[20:21], v[20:21], v[168:169]
	v_pk_add_f32 v[14:15], v[14:15], v[154:155]
	v_pk_add_f32 v[10:11], v[10:11], v[158:159]
	v_pk_add_f32 v[16:17], v[16:17], v[156:157]
	v_pk_add_f32 v[12:13], v[12:13], v[160:161]
	v_pk_add_f32 v[6:7], v[6:7], v[162:163]
	v_pk_add_f32 v[2:3], v[2:3], v[166:167]
	v_pk_add_f32 v[8:9], v[8:9], v[164:165]
	v_pk_add_f32 v[4:5], v[4:5], v[168:169]
	global_load_dwordx4 v[154:157], v[142:143], off offset:256
	global_load_dwordx4 v[158:161], v[144:145], off offset:256
	s_mov_b64 s[58:59], 0x8000
	v_lshl_add_u64 v[142:143], v[142:143], 0, s[58:59]
	s_mov_b64 s[58:59], 0x4000
	v_lshl_add_u64 v[144:145], v[144:145], 0, s[58:59]
	global_load_dwordx4 v[162:165], v[142:143], off
	global_load_dwordx4 v[166:169], v[144:145], off
	s_waitcnt vmcnt(4)
	v_lshlrev_b32_e32 v178, 16, v170
	v_and_b32_e32 v170, 0xffff0000, v170
	v_lshlrev_b32_e32 v179, 16, v174
	v_and_b32_e32 v174, 0xffff0000, v174
	v_mul_f32_e32 v126, 0xbfb8aa3b, v126
	v_mul_f32_e32 v127, 0xbfb8aa3b, v127
	v_mul_f32_e32 v180, 0xbfb8aa3b, v179
	v_mul_f32_e32 v181, 0xbfb8aa3b, v174
	v_exp_f32_e32 v126, v126
	v_exp_f32_e32 v127, v127
	v_exp_f32_e32 v180, v180
	v_exp_f32_e32 v181, v181
	v_add_f32_e32 v126, 1.0, v126
	v_add_f32_e32 v127, 1.0, v127
	v_add_f32_e32 v180, 1.0, v180
	v_add_f32_e32 v181, 1.0, v181
	v_rcp_f32_e32 v126, v126
	v_rcp_f32_e32 v127, v127
	v_rcp_f32_e32 v180, v180
	v_rcp_f32_e32 v181, v181
	v_mul_f32_e32 v126, v126, v178
	v_mul_f32_e32 v127, v127, v170
	v_mul_f32_e32 v180, v180, v179
	v_mul_f32_e32 v181, v181, v174
	v_mul_f32_e32 v126, v126, v180
	v_mul_f32_e32 v127, v127, v181
	v_lshlrev_b32_e32 v178, 16, v171
	v_and_b32_e32 v171, 0xffff0000, v171
	v_lshlrev_b32_e32 v179, 16, v175
	v_and_b32_e32 v175, 0xffff0000, v175
	v_mul_f32_e32 v128, 0xbfb8aa3b, v128
	v_mul_f32_e32 v129, 0xbfb8aa3b, v129
	v_mul_f32_e32 v180, 0xbfb8aa3b, v179
	v_mul_f32_e32 v181, 0xbfb8aa3b, v175
	v_exp_f32_e32 v128, v128
	v_exp_f32_e32 v129, v129
	v_exp_f32_e32 v180, v180
	v_exp_f32_e32 v181, v181
	v_add_f32_e32 v128, 1.0, v128
	v_add_f32_e32 v129, 1.0, v129
	v_add_f32_e32 v180, 1.0, v180
	v_add_f32_e32 v181, 1.0, v181
	v_rcp_f32_e32 v128, v128
	v_rcp_f32_e32 v129, v129
	v_rcp_f32_e32 v180, v180
	v_rcp_f32_e32 v181, v181
	v_mul_f32_e32 v128, v128, v178
	v_mul_f32_e32 v129, v129, v171
	v_mul_f32_e32 v180, v180, v179
	v_mul_f32_e32 v181, v181, v175
	v_mul_f32_e32 v128, v128, v180
	v_mul_f32_e32 v129, v129, v181
	v_lshlrev_b32_e32 v178, 16, v172
	v_and_b32_e32 v172, 0xffff0000, v172
	v_lshlrev_b32_e32 v179, 16, v176
	v_and_b32_e32 v176, 0xffff0000, v176
	v_mul_f32_e32 v122, 0xbfb8aa3b, v122
	v_mul_f32_e32 v123, 0xbfb8aa3b, v123
	v_mul_f32_e32 v180, 0xbfb8aa3b, v179
	v_mul_f32_e32 v181, 0xbfb8aa3b, v176
	v_exp_f32_e32 v122, v122
	v_exp_f32_e32 v123, v123
	v_exp_f32_e32 v180, v180
	v_exp_f32_e32 v181, v181
	v_add_f32_e32 v122, 1.0, v122
	v_add_f32_e32 v123, 1.0, v123
	v_add_f32_e32 v180, 1.0, v180
	v_add_f32_e32 v181, 1.0, v181
	v_rcp_f32_e32 v122, v122
	v_rcp_f32_e32 v123, v123
	v_rcp_f32_e32 v180, v180
	v_rcp_f32_e32 v181, v181
	v_mul_f32_e32 v122, v122, v178
	v_mul_f32_e32 v123, v123, v172
	v_mul_f32_e32 v180, v180, v179
	v_mul_f32_e32 v181, v181, v176
	v_mul_f32_e32 v122, v122, v180
	v_mul_f32_e32 v123, v123, v181
	v_lshlrev_b32_e32 v178, 16, v173
	v_and_b32_e32 v173, 0xffff0000, v173
	v_lshlrev_b32_e32 v179, 16, v177
	v_and_b32_e32 v177, 0xffff0000, v177
	v_mul_f32_e32 v124, 0xbfb8aa3b, v124
	v_mul_f32_e32 v125, 0xbfb8aa3b, v125
	v_mul_f32_e32 v180, 0xbfb8aa3b, v179
	v_mul_f32_e32 v181, 0xbfb8aa3b, v177
	v_exp_f32_e32 v124, v124
	v_exp_f32_e32 v125, v125
	v_exp_f32_e32 v180, v180
	v_exp_f32_e32 v181, v181
	v_add_f32_e32 v124, 1.0, v124
	v_add_f32_e32 v125, 1.0, v125
	v_add_f32_e32 v180, 1.0, v180
	v_add_f32_e32 v181, 1.0, v181
	v_rcp_f32_e32 v124, v124
	v_rcp_f32_e32 v125, v125
	v_rcp_f32_e32 v180, v180
	v_rcp_f32_e32 v181, v181
	v_mul_f32_e32 v124, v124, v178
	v_mul_f32_e32 v125, v125, v173
	v_mul_f32_e32 v180, v180, v179
	v_mul_f32_e32 v181, v181, v177
	v_mul_f32_e32 v124, v124, v180
	v_mul_f32_e32 v125, v125, v181
	v_cvt_pk_bf16_f32 v126, v126, v127
	v_cvt_pk_bf16_f32 v127, v128, v129
	v_cvt_pk_bf16_f32 v128, v122, v123
	v_cvt_pk_bf16_f32 v129, v124, v125
	global_store_dwordx4 v[146:147], v[126:129], off
	global_load_dwordx4 v[170:173], v[142:143], off offset:256
	global_load_dwordx4 v[174:177], v[144:145], off offset:256
	s_waitcnt vmcnt(5)
	v_lshlrev_b32_e32 v178, 16, v154
	v_and_b32_e32 v154, 0xffff0000, v154
	v_lshlrev_b32_e32 v179, 16, v158
	v_and_b32_e32 v158, 0xffff0000, v158
	v_mul_f32_e32 v118, 0xbfb8aa3b, v118
	v_mul_f32_e32 v119, 0xbfb8aa3b, v119
	v_mul_f32_e32 v180, 0xbfb8aa3b, v179
	v_mul_f32_e32 v181, 0xbfb8aa3b, v158
	v_exp_f32_e32 v118, v118
	v_exp_f32_e32 v119, v119
	v_exp_f32_e32 v180, v180
	v_exp_f32_e32 v181, v181
	v_add_f32_e32 v118, 1.0, v118
	v_add_f32_e32 v119, 1.0, v119
	v_add_f32_e32 v180, 1.0, v180
	v_add_f32_e32 v181, 1.0, v181
	v_rcp_f32_e32 v118, v118
	v_rcp_f32_e32 v119, v119
	v_rcp_f32_e32 v180, v180
	v_rcp_f32_e32 v181, v181
	v_mul_f32_e32 v118, v118, v178
	v_mul_f32_e32 v119, v119, v154
	v_mul_f32_e32 v180, v180, v179
	v_mul_f32_e32 v181, v181, v158
	v_mul_f32_e32 v118, v118, v180
	v_mul_f32_e32 v119, v119, v181
	v_lshlrev_b32_e32 v178, 16, v155
	v_and_b32_e32 v155, 0xffff0000, v155
	v_lshlrev_b32_e32 v179, 16, v159
	v_and_b32_e32 v159, 0xffff0000, v159
	v_mul_f32_e32 v120, 0xbfb8aa3b, v120
	v_mul_f32_e32 v121, 0xbfb8aa3b, v121
	v_mul_f32_e32 v180, 0xbfb8aa3b, v179
	v_mul_f32_e32 v181, 0xbfb8aa3b, v159
	v_exp_f32_e32 v120, v120
	v_exp_f32_e32 v121, v121
	v_exp_f32_e32 v180, v180
	v_exp_f32_e32 v181, v181
	v_add_f32_e32 v120, 1.0, v120
	v_add_f32_e32 v121, 1.0, v121
	v_add_f32_e32 v180, 1.0, v180
	v_add_f32_e32 v181, 1.0, v181
	v_rcp_f32_e32 v120, v120
	v_rcp_f32_e32 v121, v121
	v_rcp_f32_e32 v180, v180
	v_rcp_f32_e32 v181, v181
	v_mul_f32_e32 v120, v120, v178
	v_mul_f32_e32 v121, v121, v155
	v_mul_f32_e32 v180, v180, v179
	v_mul_f32_e32 v181, v181, v159
	v_mul_f32_e32 v120, v120, v180
	v_mul_f32_e32 v121, v121, v181
	v_lshlrev_b32_e32 v178, 16, v156
	v_and_b32_e32 v156, 0xffff0000, v156
	v_lshlrev_b32_e32 v179, 16, v160
	v_and_b32_e32 v160, 0xffff0000, v160
	v_mul_f32_e32 v114, 0xbfb8aa3b, v114
	v_mul_f32_e32 v115, 0xbfb8aa3b, v115
	v_mul_f32_e32 v180, 0xbfb8aa3b, v179
	v_mul_f32_e32 v181, 0xbfb8aa3b, v160
	v_exp_f32_e32 v114, v114
	v_exp_f32_e32 v115, v115
	v_exp_f32_e32 v180, v180
	v_exp_f32_e32 v181, v181
	v_add_f32_e32 v114, 1.0, v114
	v_add_f32_e32 v115, 1.0, v115
	v_add_f32_e32 v180, 1.0, v180
	v_add_f32_e32 v181, 1.0, v181
	v_rcp_f32_e32 v114, v114
	v_rcp_f32_e32 v115, v115
	v_rcp_f32_e32 v180, v180
	v_rcp_f32_e32 v181, v181
	v_mul_f32_e32 v114, v114, v178
	v_mul_f32_e32 v115, v115, v156
	v_mul_f32_e32 v180, v180, v179
	v_mul_f32_e32 v181, v181, v160
	v_mul_f32_e32 v114, v114, v180
	v_mul_f32_e32 v115, v115, v181
	v_lshlrev_b32_e32 v178, 16, v157
	v_and_b32_e32 v157, 0xffff0000, v157
	v_lshlrev_b32_e32 v179, 16, v161
	v_and_b32_e32 v161, 0xffff0000, v161
	v_mul_f32_e32 v116, 0xbfb8aa3b, v116
	v_mul_f32_e32 v117, 0xbfb8aa3b, v117
	v_mul_f32_e32 v180, 0xbfb8aa3b, v179
	v_mul_f32_e32 v181, 0xbfb8aa3b, v161
	v_exp_f32_e32 v116, v116
	v_exp_f32_e32 v117, v117
	v_exp_f32_e32 v180, v180
	v_exp_f32_e32 v181, v181
	v_add_f32_e32 v116, 1.0, v116
	v_add_f32_e32 v117, 1.0, v117
	v_add_f32_e32 v180, 1.0, v180
	v_add_f32_e32 v181, 1.0, v181
	v_rcp_f32_e32 v116, v116
	v_rcp_f32_e32 v117, v117
	v_rcp_f32_e32 v180, v180
	v_rcp_f32_e32 v181, v181
	v_mul_f32_e32 v116, v116, v178
	v_mul_f32_e32 v117, v117, v157
	v_mul_f32_e32 v180, v180, v179
	v_mul_f32_e32 v181, v181, v161
	v_mul_f32_e32 v116, v116, v180
	v_mul_f32_e32 v117, v117, v181
	v_cvt_pk_bf16_f32 v118, v118, v119
	v_cvt_pk_bf16_f32 v119, v120, v121
	v_cvt_pk_bf16_f32 v120, v114, v115
	v_cvt_pk_bf16_f32 v121, v116, v117
	global_store_dwordx4 v[146:147], v[118:121], off offset:256
	s_mov_b64 s[58:59], 0x20000
	v_lshl_add_u64 v[146:147], v[146:147], 0, s[58:59]
	s_mov_b64 s[58:59], 0x8000
	v_lshl_add_u64 v[142:143], v[142:143], 0, s[58:59]
	s_mov_b64 s[58:59], 0x4000
	v_lshl_add_u64 v[144:145], v[144:145], 0, s[58:59]
	global_load_dwordx4 v[154:157], v[142:143], off
	global_load_dwordx4 v[158:161], v[144:145], off
	s_waitcnt vmcnt(6)
	v_lshlrev_b32_e32 v178, 16, v162
	v_and_b32_e32 v162, 0xffff0000, v162
	v_lshlrev_b32_e32 v179, 16, v166
	v_and_b32_e32 v166, 0xffff0000, v166
	v_mul_f32_e32 v110, 0xbfb8aa3b, v110
	v_mul_f32_e32 v111, 0xbfb8aa3b, v111
	v_mul_f32_e32 v180, 0xbfb8aa3b, v179
	v_mul_f32_e32 v181, 0xbfb8aa3b, v166
	v_exp_f32_e32 v110, v110
	v_exp_f32_e32 v111, v111
	v_exp_f32_e32 v180, v180
	v_exp_f32_e32 v181, v181
	v_add_f32_e32 v110, 1.0, v110
	v_add_f32_e32 v111, 1.0, v111
	v_add_f32_e32 v180, 1.0, v180
	v_add_f32_e32 v181, 1.0, v181
	v_rcp_f32_e32 v110, v110
	v_rcp_f32_e32 v111, v111
	v_rcp_f32_e32 v180, v180
	v_rcp_f32_e32 v181, v181
	v_mul_f32_e32 v110, v110, v178
	v_mul_f32_e32 v111, v111, v162
	v_mul_f32_e32 v180, v180, v179
	v_mul_f32_e32 v181, v181, v166
	v_mul_f32_e32 v110, v110, v180
	v_mul_f32_e32 v111, v111, v181
	v_lshlrev_b32_e32 v178, 16, v163
	v_and_b32_e32 v163, 0xffff0000, v163
	v_lshlrev_b32_e32 v179, 16, v167
	v_and_b32_e32 v167, 0xffff0000, v167
	v_mul_f32_e32 v112, 0xbfb8aa3b, v112
	v_mul_f32_e32 v113, 0xbfb8aa3b, v113
	v_mul_f32_e32 v180, 0xbfb8aa3b, v179
	v_mul_f32_e32 v181, 0xbfb8aa3b, v167
	v_exp_f32_e32 v112, v112
	v_exp_f32_e32 v113, v113
	v_exp_f32_e32 v180, v180
	v_exp_f32_e32 v181, v181
	v_add_f32_e32 v112, 1.0, v112
	v_add_f32_e32 v113, 1.0, v113
	v_add_f32_e32 v180, 1.0, v180
	v_add_f32_e32 v181, 1.0, v181
	v_rcp_f32_e32 v112, v112
	v_rcp_f32_e32 v113, v113
	v_rcp_f32_e32 v180, v180
	v_rcp_f32_e32 v181, v181
	v_mul_f32_e32 v112, v112, v178
	v_mul_f32_e32 v113, v113, v163
	v_mul_f32_e32 v180, v180, v179
	v_mul_f32_e32 v181, v181, v167
	v_mul_f32_e32 v112, v112, v180
	v_mul_f32_e32 v113, v113, v181
	v_lshlrev_b32_e32 v178, 16, v164
	v_and_b32_e32 v164, 0xffff0000, v164
	v_lshlrev_b32_e32 v179, 16, v168
	v_and_b32_e32 v168, 0xffff0000, v168
	v_mul_f32_e32 v106, 0xbfb8aa3b, v106
	v_mul_f32_e32 v107, 0xbfb8aa3b, v107
	v_mul_f32_e32 v180, 0xbfb8aa3b, v179
	v_mul_f32_e32 v181, 0xbfb8aa3b, v168
	v_exp_f32_e32 v106, v106
	v_exp_f32_e32 v107, v107
	v_exp_f32_e32 v180, v180
	v_exp_f32_e32 v181, v181
	v_add_f32_e32 v106, 1.0, v106
	v_add_f32_e32 v107, 1.0, v107
	v_add_f32_e32 v180, 1.0, v180
	v_add_f32_e32 v181, 1.0, v181
	v_rcp_f32_e32 v106, v106
	v_rcp_f32_e32 v107, v107
	v_rcp_f32_e32 v180, v180
	v_rcp_f32_e32 v181, v181
	v_mul_f32_e32 v106, v106, v178
	v_mul_f32_e32 v107, v107, v164
	v_mul_f32_e32 v180, v180, v179
	v_mul_f32_e32 v181, v181, v168
	v_mul_f32_e32 v106, v106, v180
	v_mul_f32_e32 v107, v107, v181
	v_lshlrev_b32_e32 v178, 16, v165
	v_and_b32_e32 v165, 0xffff0000, v165
	v_lshlrev_b32_e32 v179, 16, v169
	v_and_b32_e32 v169, 0xffff0000, v169
	v_mul_f32_e32 v108, 0xbfb8aa3b, v108
	v_mul_f32_e32 v109, 0xbfb8aa3b, v109
	v_mul_f32_e32 v180, 0xbfb8aa3b, v179
	v_mul_f32_e32 v181, 0xbfb8aa3b, v169
	v_exp_f32_e32 v108, v108
	v_exp_f32_e32 v109, v109
	v_exp_f32_e32 v180, v180
	v_exp_f32_e32 v181, v181
	v_add_f32_e32 v108, 1.0, v108
	v_add_f32_e32 v109, 1.0, v109
	v_add_f32_e32 v180, 1.0, v180
	v_add_f32_e32 v181, 1.0, v181
	v_rcp_f32_e32 v108, v108
	v_rcp_f32_e32 v109, v109
	v_rcp_f32_e32 v180, v180
	v_rcp_f32_e32 v181, v181
	v_mul_f32_e32 v108, v108, v178
	v_mul_f32_e32 v109, v109, v165
	v_mul_f32_e32 v180, v180, v179
	v_mul_f32_e32 v181, v181, v169
	v_mul_f32_e32 v108, v108, v180
	v_mul_f32_e32 v109, v109, v181
	v_cvt_pk_bf16_f32 v110, v110, v111
	v_cvt_pk_bf16_f32 v111, v112, v113
	v_cvt_pk_bf16_f32 v112, v106, v107
	v_cvt_pk_bf16_f32 v113, v108, v109
	global_store_dwordx4 v[146:147], v[110:113], off
	global_load_dwordx4 v[162:165], v[142:143], off offset:256
	global_load_dwordx4 v[166:169], v[144:145], off offset:256
	s_waitcnt vmcnt(6)
	v_lshlrev_b32_e32 v178, 16, v170
	v_and_b32_e32 v170, 0xffff0000, v170
	v_lshlrev_b32_e32 v179, 16, v174
	v_and_b32_e32 v174, 0xffff0000, v174
	v_mul_f32_e32 v102, 0xbfb8aa3b, v102
	v_mul_f32_e32 v103, 0xbfb8aa3b, v103
	v_mul_f32_e32 v180, 0xbfb8aa3b, v179
	v_mul_f32_e32 v181, 0xbfb8aa3b, v174
	v_exp_f32_e32 v102, v102
	v_exp_f32_e32 v103, v103
	v_exp_f32_e32 v180, v180
	v_exp_f32_e32 v181, v181
	v_add_f32_e32 v102, 1.0, v102
	v_add_f32_e32 v103, 1.0, v103
	v_add_f32_e32 v180, 1.0, v180
	v_add_f32_e32 v181, 1.0, v181
	v_rcp_f32_e32 v102, v102
	v_rcp_f32_e32 v103, v103
	v_rcp_f32_e32 v180, v180
	v_rcp_f32_e32 v181, v181
	v_mul_f32_e32 v102, v102, v178
	v_mul_f32_e32 v103, v103, v170
	v_mul_f32_e32 v180, v180, v179
	v_mul_f32_e32 v181, v181, v174
	v_mul_f32_e32 v102, v102, v180
	v_mul_f32_e32 v103, v103, v181
	v_lshlrev_b32_e32 v178, 16, v171
	v_and_b32_e32 v171, 0xffff0000, v171
	v_lshlrev_b32_e32 v179, 16, v175
	v_and_b32_e32 v175, 0xffff0000, v175
	v_mul_f32_e32 v104, 0xbfb8aa3b, v104
	v_mul_f32_e32 v105, 0xbfb8aa3b, v105
	v_mul_f32_e32 v180, 0xbfb8aa3b, v179
	v_mul_f32_e32 v181, 0xbfb8aa3b, v175
	v_exp_f32_e32 v104, v104
	v_exp_f32_e32 v105, v105
	v_exp_f32_e32 v180, v180
	v_exp_f32_e32 v181, v181
	v_add_f32_e32 v104, 1.0, v104
	v_add_f32_e32 v105, 1.0, v105
	v_add_f32_e32 v180, 1.0, v180
	v_add_f32_e32 v181, 1.0, v181
	v_rcp_f32_e32 v104, v104
	v_rcp_f32_e32 v105, v105
	v_rcp_f32_e32 v180, v180
	v_rcp_f32_e32 v181, v181
	v_mul_f32_e32 v104, v104, v178
	v_mul_f32_e32 v105, v105, v171
	v_mul_f32_e32 v180, v180, v179
	v_mul_f32_e32 v181, v181, v175
	v_mul_f32_e32 v104, v104, v180
	v_mul_f32_e32 v105, v105, v181
	v_lshlrev_b32_e32 v178, 16, v172
	v_and_b32_e32 v172, 0xffff0000, v172
	v_lshlrev_b32_e32 v179, 16, v176
	v_and_b32_e32 v176, 0xffff0000, v176
	v_mul_f32_e32 v98, 0xbfb8aa3b, v98
	v_mul_f32_e32 v99, 0xbfb8aa3b, v99
	v_mul_f32_e32 v180, 0xbfb8aa3b, v179
	v_mul_f32_e32 v181, 0xbfb8aa3b, v176
	v_exp_f32_e32 v98, v98
	v_exp_f32_e32 v99, v99
	v_exp_f32_e32 v180, v180
	v_exp_f32_e32 v181, v181
	v_add_f32_e32 v98, 1.0, v98
	v_add_f32_e32 v99, 1.0, v99
	v_add_f32_e32 v180, 1.0, v180
	v_add_f32_e32 v181, 1.0, v181
	v_rcp_f32_e32 v98, v98
	v_rcp_f32_e32 v99, v99
	v_rcp_f32_e32 v180, v180
	v_rcp_f32_e32 v181, v181
	v_mul_f32_e32 v98, v98, v178
	v_mul_f32_e32 v99, v99, v172
	v_mul_f32_e32 v180, v180, v179
	v_mul_f32_e32 v181, v181, v176
	v_mul_f32_e32 v98, v98, v180
	v_mul_f32_e32 v99, v99, v181
	v_lshlrev_b32_e32 v178, 16, v173
	v_and_b32_e32 v173, 0xffff0000, v173
	v_lshlrev_b32_e32 v179, 16, v177
	v_and_b32_e32 v177, 0xffff0000, v177
	v_mul_f32_e32 v100, 0xbfb8aa3b, v100
	v_mul_f32_e32 v101, 0xbfb8aa3b, v101
	v_mul_f32_e32 v180, 0xbfb8aa3b, v179
	v_mul_f32_e32 v181, 0xbfb8aa3b, v177
	v_exp_f32_e32 v100, v100
	v_exp_f32_e32 v101, v101
	v_exp_f32_e32 v180, v180
	v_exp_f32_e32 v181, v181
	v_add_f32_e32 v100, 1.0, v100
	v_add_f32_e32 v101, 1.0, v101
	v_add_f32_e32 v180, 1.0, v180
	v_add_f32_e32 v181, 1.0, v181
	v_rcp_f32_e32 v100, v100
	v_rcp_f32_e32 v101, v101
	v_rcp_f32_e32 v180, v180
	v_rcp_f32_e32 v181, v181
	v_mul_f32_e32 v100, v100, v178
	v_mul_f32_e32 v101, v101, v173
	v_mul_f32_e32 v180, v180, v179
	v_mul_f32_e32 v181, v181, v177
	v_mul_f32_e32 v100, v100, v180
	v_mul_f32_e32 v101, v101, v181
	v_cvt_pk_bf16_f32 v102, v102, v103
	v_cvt_pk_bf16_f32 v103, v104, v105
	v_cvt_pk_bf16_f32 v104, v98, v99
	v_cvt_pk_bf16_f32 v105, v100, v101
	global_store_dwordx4 v[146:147], v[102:105], off offset:256
	s_mov_b64 s[58:59], 0x20000
	v_lshl_add_u64 v[146:147], v[146:147], 0, s[58:59]
	s_mov_b64 s[58:59], 0x8000
	v_lshl_add_u64 v[142:143], v[142:143], 0, s[58:59]
	s_mov_b64 s[58:59], 0x4000
	v_lshl_add_u64 v[144:145], v[144:145], 0, s[58:59]
	global_load_dwordx4 v[170:173], v[142:143], off
	global_load_dwordx4 v[174:177], v[144:145], off
	s_waitcnt vmcnt(6)
	v_lshlrev_b32_e32 v178, 16, v154
	v_and_b32_e32 v154, 0xffff0000, v154
	v_lshlrev_b32_e32 v179, 16, v158
	v_and_b32_e32 v158, 0xffff0000, v158
	v_mul_f32_e32 v94, 0xbfb8aa3b, v94
	v_mul_f32_e32 v95, 0xbfb8aa3b, v95
	v_mul_f32_e32 v180, 0xbfb8aa3b, v179
	v_mul_f32_e32 v181, 0xbfb8aa3b, v158
	v_exp_f32_e32 v94, v94
	v_exp_f32_e32 v95, v95
	v_exp_f32_e32 v180, v180
	v_exp_f32_e32 v181, v181
	v_add_f32_e32 v94, 1.0, v94
	v_add_f32_e32 v95, 1.0, v95
	v_add_f32_e32 v180, 1.0, v180
	v_add_f32_e32 v181, 1.0, v181
	v_rcp_f32_e32 v94, v94
	v_rcp_f32_e32 v95, v95
	v_rcp_f32_e32 v180, v180
	v_rcp_f32_e32 v181, v181
	v_mul_f32_e32 v94, v94, v178
	v_mul_f32_e32 v95, v95, v154
	v_mul_f32_e32 v180, v180, v179
	v_mul_f32_e32 v181, v181, v158
	v_mul_f32_e32 v94, v94, v180
	v_mul_f32_e32 v95, v95, v181
	v_lshlrev_b32_e32 v178, 16, v155
	v_and_b32_e32 v155, 0xffff0000, v155
	v_lshlrev_b32_e32 v179, 16, v159
	v_and_b32_e32 v159, 0xffff0000, v159
	v_mul_f32_e32 v96, 0xbfb8aa3b, v96
	v_mul_f32_e32 v97, 0xbfb8aa3b, v97
	v_mul_f32_e32 v180, 0xbfb8aa3b, v179
	v_mul_f32_e32 v181, 0xbfb8aa3b, v159
	v_exp_f32_e32 v96, v96
	v_exp_f32_e32 v97, v97
	v_exp_f32_e32 v180, v180
	v_exp_f32_e32 v181, v181
	v_add_f32_e32 v96, 1.0, v96
	v_add_f32_e32 v97, 1.0, v97
	v_add_f32_e32 v180, 1.0, v180
	v_add_f32_e32 v181, 1.0, v181
	v_rcp_f32_e32 v96, v96
	v_rcp_f32_e32 v97, v97
	v_rcp_f32_e32 v180, v180
	v_rcp_f32_e32 v181, v181
	v_mul_f32_e32 v96, v96, v178
	v_mul_f32_e32 v97, v97, v155
	v_mul_f32_e32 v180, v180, v179
	v_mul_f32_e32 v181, v181, v159
	v_mul_f32_e32 v96, v96, v180
	v_mul_f32_e32 v97, v97, v181
	v_lshlrev_b32_e32 v178, 16, v156
	v_and_b32_e32 v156, 0xffff0000, v156
	v_lshlrev_b32_e32 v179, 16, v160
	v_and_b32_e32 v160, 0xffff0000, v160
	v_mul_f32_e32 v90, 0xbfb8aa3b, v90
	v_mul_f32_e32 v91, 0xbfb8aa3b, v91
	v_mul_f32_e32 v180, 0xbfb8aa3b, v179
	v_mul_f32_e32 v181, 0xbfb8aa3b, v160
	v_exp_f32_e32 v90, v90
	v_exp_f32_e32 v91, v91
	v_exp_f32_e32 v180, v180
	v_exp_f32_e32 v181, v181
	v_add_f32_e32 v90, 1.0, v90
	v_add_f32_e32 v91, 1.0, v91
	v_add_f32_e32 v180, 1.0, v180
	v_add_f32_e32 v181, 1.0, v181
	v_rcp_f32_e32 v90, v90
	v_rcp_f32_e32 v91, v91
	v_rcp_f32_e32 v180, v180
	v_rcp_f32_e32 v181, v181
	v_mul_f32_e32 v90, v90, v178
	v_mul_f32_e32 v91, v91, v156
	v_mul_f32_e32 v180, v180, v179
	v_mul_f32_e32 v181, v181, v160
	v_mul_f32_e32 v90, v90, v180
	v_mul_f32_e32 v91, v91, v181
	v_lshlrev_b32_e32 v178, 16, v157
	v_and_b32_e32 v157, 0xffff0000, v157
	v_lshlrev_b32_e32 v179, 16, v161
	v_and_b32_e32 v161, 0xffff0000, v161
	v_mul_f32_e32 v92, 0xbfb8aa3b, v92
	v_mul_f32_e32 v93, 0xbfb8aa3b, v93
	v_mul_f32_e32 v180, 0xbfb8aa3b, v179
	v_mul_f32_e32 v181, 0xbfb8aa3b, v161
	v_exp_f32_e32 v92, v92
	v_exp_f32_e32 v93, v93
	v_exp_f32_e32 v180, v180
	v_exp_f32_e32 v181, v181
	v_add_f32_e32 v92, 1.0, v92
	v_add_f32_e32 v93, 1.0, v93
	v_add_f32_e32 v180, 1.0, v180
	v_add_f32_e32 v181, 1.0, v181
	v_rcp_f32_e32 v92, v92
	v_rcp_f32_e32 v93, v93
	v_rcp_f32_e32 v180, v180
	v_rcp_f32_e32 v181, v181
	v_mul_f32_e32 v92, v92, v178
	v_mul_f32_e32 v93, v93, v157
	v_mul_f32_e32 v180, v180, v179
	v_mul_f32_e32 v181, v181, v161
	v_mul_f32_e32 v92, v92, v180
	v_mul_f32_e32 v93, v93, v181
	v_cvt_pk_bf16_f32 v94, v94, v95
	v_cvt_pk_bf16_f32 v95, v96, v97
	v_cvt_pk_bf16_f32 v96, v90, v91
	v_cvt_pk_bf16_f32 v97, v92, v93
	global_store_dwordx4 v[146:147], v[94:97], off
	global_load_dwordx4 v[154:157], v[142:143], off offset:256
	global_load_dwordx4 v[158:161], v[144:145], off offset:256
	s_waitcnt vmcnt(6)
	v_lshlrev_b32_e32 v178, 16, v162
	v_and_b32_e32 v162, 0xffff0000, v162
	v_lshlrev_b32_e32 v179, 16, v166
	v_and_b32_e32 v166, 0xffff0000, v166
	v_mul_f32_e32 v86, 0xbfb8aa3b, v86
	v_mul_f32_e32 v87, 0xbfb8aa3b, v87
	v_mul_f32_e32 v180, 0xbfb8aa3b, v179
	v_mul_f32_e32 v181, 0xbfb8aa3b, v166
	v_exp_f32_e32 v86, v86
	v_exp_f32_e32 v87, v87
	v_exp_f32_e32 v180, v180
	v_exp_f32_e32 v181, v181
	v_add_f32_e32 v86, 1.0, v86
	v_add_f32_e32 v87, 1.0, v87
	v_add_f32_e32 v180, 1.0, v180
	v_add_f32_e32 v181, 1.0, v181
	v_rcp_f32_e32 v86, v86
	v_rcp_f32_e32 v87, v87
	v_rcp_f32_e32 v180, v180
	v_rcp_f32_e32 v181, v181
	v_mul_f32_e32 v86, v86, v178
	v_mul_f32_e32 v87, v87, v162
	v_mul_f32_e32 v180, v180, v179
	v_mul_f32_e32 v181, v181, v166
	v_mul_f32_e32 v86, v86, v180
	v_mul_f32_e32 v87, v87, v181
	v_lshlrev_b32_e32 v178, 16, v163
	v_and_b32_e32 v163, 0xffff0000, v163
	v_lshlrev_b32_e32 v179, 16, v167
	v_and_b32_e32 v167, 0xffff0000, v167
	v_mul_f32_e32 v88, 0xbfb8aa3b, v88
	v_mul_f32_e32 v89, 0xbfb8aa3b, v89
	v_mul_f32_e32 v180, 0xbfb8aa3b, v179
	v_mul_f32_e32 v181, 0xbfb8aa3b, v167
	v_exp_f32_e32 v88, v88
	v_exp_f32_e32 v89, v89
	v_exp_f32_e32 v180, v180
	v_exp_f32_e32 v181, v181
	v_add_f32_e32 v88, 1.0, v88
	v_add_f32_e32 v89, 1.0, v89
	v_add_f32_e32 v180, 1.0, v180
	v_add_f32_e32 v181, 1.0, v181
	v_rcp_f32_e32 v88, v88
	v_rcp_f32_e32 v89, v89
	v_rcp_f32_e32 v180, v180
	v_rcp_f32_e32 v181, v181
	v_mul_f32_e32 v88, v88, v178
	v_mul_f32_e32 v89, v89, v163
	v_mul_f32_e32 v180, v180, v179
	v_mul_f32_e32 v181, v181, v167
	v_mul_f32_e32 v88, v88, v180
	v_mul_f32_e32 v89, v89, v181
	v_lshlrev_b32_e32 v178, 16, v164
	v_and_b32_e32 v164, 0xffff0000, v164
	v_lshlrev_b32_e32 v179, 16, v168
	v_and_b32_e32 v168, 0xffff0000, v168
	v_mul_f32_e32 v82, 0xbfb8aa3b, v82
	v_mul_f32_e32 v83, 0xbfb8aa3b, v83
	v_mul_f32_e32 v180, 0xbfb8aa3b, v179
	v_mul_f32_e32 v181, 0xbfb8aa3b, v168
	v_exp_f32_e32 v82, v82
	v_exp_f32_e32 v83, v83
	v_exp_f32_e32 v180, v180
	v_exp_f32_e32 v181, v181
	v_add_f32_e32 v82, 1.0, v82
	v_add_f32_e32 v83, 1.0, v83
	v_add_f32_e32 v180, 1.0, v180
	v_add_f32_e32 v181, 1.0, v181
	v_rcp_f32_e32 v82, v82
	v_rcp_f32_e32 v83, v83
	v_rcp_f32_e32 v180, v180
	v_rcp_f32_e32 v181, v181
	v_mul_f32_e32 v82, v82, v178
	v_mul_f32_e32 v83, v83, v164
	v_mul_f32_e32 v180, v180, v179
	v_mul_f32_e32 v181, v181, v168
	v_mul_f32_e32 v82, v82, v180
	v_mul_f32_e32 v83, v83, v181
	v_lshlrev_b32_e32 v178, 16, v165
	v_and_b32_e32 v165, 0xffff0000, v165
	v_lshlrev_b32_e32 v179, 16, v169
	v_and_b32_e32 v169, 0xffff0000, v169
	v_mul_f32_e32 v84, 0xbfb8aa3b, v84
	v_mul_f32_e32 v85, 0xbfb8aa3b, v85
	v_mul_f32_e32 v180, 0xbfb8aa3b, v179
	v_mul_f32_e32 v181, 0xbfb8aa3b, v169
	v_exp_f32_e32 v84, v84
	v_exp_f32_e32 v85, v85
	v_exp_f32_e32 v180, v180
	v_exp_f32_e32 v181, v181
	v_add_f32_e32 v84, 1.0, v84
	v_add_f32_e32 v85, 1.0, v85
	v_add_f32_e32 v180, 1.0, v180
	v_add_f32_e32 v181, 1.0, v181
	v_rcp_f32_e32 v84, v84
	v_rcp_f32_e32 v85, v85
	v_rcp_f32_e32 v180, v180
	v_rcp_f32_e32 v181, v181
	v_mul_f32_e32 v84, v84, v178
	v_mul_f32_e32 v85, v85, v165
	v_mul_f32_e32 v180, v180, v179
	v_mul_f32_e32 v181, v181, v169
	v_mul_f32_e32 v84, v84, v180
	v_mul_f32_e32 v85, v85, v181
	v_cvt_pk_bf16_f32 v86, v86, v87
	v_cvt_pk_bf16_f32 v87, v88, v89
	v_cvt_pk_bf16_f32 v88, v82, v83
	v_cvt_pk_bf16_f32 v89, v84, v85
	global_store_dwordx4 v[146:147], v[86:89], off offset:256
	s_mov_b64 s[58:59], 0x20000
	v_lshl_add_u64 v[146:147], v[146:147], 0, s[58:59]
	s_mov_b64 s[58:59], 0x28000
	v_lshl_add_u64 v[142:143], v[142:143], 0, s[58:59]
	s_mov_b64 s[58:59], 0x14000
	v_lshl_add_u64 v[144:145], v[144:145], 0, s[58:59]
	global_load_dwordx4 v[162:165], v[142:143], off
	global_load_dwordx4 v[166:169], v[144:145], off
	s_waitcnt vmcnt(6)
	v_lshlrev_b32_e32 v178, 16, v170
	v_and_b32_e32 v170, 0xffff0000, v170
	v_lshlrev_b32_e32 v179, 16, v174
	v_and_b32_e32 v174, 0xffff0000, v174
	v_mul_f32_e32 v78, 0xbfb8aa3b, v78
	v_mul_f32_e32 v79, 0xbfb8aa3b, v79
	v_mul_f32_e32 v180, 0xbfb8aa3b, v179
	v_mul_f32_e32 v181, 0xbfb8aa3b, v174
	v_exp_f32_e32 v78, v78
	v_exp_f32_e32 v79, v79
	v_exp_f32_e32 v180, v180
	v_exp_f32_e32 v181, v181
	v_add_f32_e32 v78, 1.0, v78
	v_add_f32_e32 v79, 1.0, v79
	v_add_f32_e32 v180, 1.0, v180
	v_add_f32_e32 v181, 1.0, v181
	v_rcp_f32_e32 v78, v78
	v_rcp_f32_e32 v79, v79
	v_rcp_f32_e32 v180, v180
	v_rcp_f32_e32 v181, v181
	v_mul_f32_e32 v78, v78, v178
	v_mul_f32_e32 v79, v79, v170
	v_mul_f32_e32 v180, v180, v179
	v_mul_f32_e32 v181, v181, v174
	v_mul_f32_e32 v78, v78, v180
	v_mul_f32_e32 v79, v79, v181
	v_lshlrev_b32_e32 v178, 16, v171
	v_and_b32_e32 v171, 0xffff0000, v171
	v_lshlrev_b32_e32 v179, 16, v175
	v_and_b32_e32 v175, 0xffff0000, v175
	v_mul_f32_e32 v80, 0xbfb8aa3b, v80
	v_mul_f32_e32 v81, 0xbfb8aa3b, v81
	v_mul_f32_e32 v180, 0xbfb8aa3b, v179
	v_mul_f32_e32 v181, 0xbfb8aa3b, v175
	v_exp_f32_e32 v80, v80
	v_exp_f32_e32 v81, v81
	v_exp_f32_e32 v180, v180
	v_exp_f32_e32 v181, v181
	v_add_f32_e32 v80, 1.0, v80
	v_add_f32_e32 v81, 1.0, v81
	v_add_f32_e32 v180, 1.0, v180
	v_add_f32_e32 v181, 1.0, v181
	v_rcp_f32_e32 v80, v80
	v_rcp_f32_e32 v81, v81
	v_rcp_f32_e32 v180, v180
	v_rcp_f32_e32 v181, v181
	v_mul_f32_e32 v80, v80, v178
	v_mul_f32_e32 v81, v81, v171
	v_mul_f32_e32 v180, v180, v179
	v_mul_f32_e32 v181, v181, v175
	v_mul_f32_e32 v80, v80, v180
	v_mul_f32_e32 v81, v81, v181
	v_lshlrev_b32_e32 v178, 16, v172
	v_and_b32_e32 v172, 0xffff0000, v172
	v_lshlrev_b32_e32 v179, 16, v176
	v_and_b32_e32 v176, 0xffff0000, v176
	v_mul_f32_e32 v74, 0xbfb8aa3b, v74
	v_mul_f32_e32 v75, 0xbfb8aa3b, v75
	v_mul_f32_e32 v180, 0xbfb8aa3b, v179
	v_mul_f32_e32 v181, 0xbfb8aa3b, v176
	v_exp_f32_e32 v74, v74
	v_exp_f32_e32 v75, v75
	v_exp_f32_e32 v180, v180
	v_exp_f32_e32 v181, v181
	v_add_f32_e32 v74, 1.0, v74
	v_add_f32_e32 v75, 1.0, v75
	v_add_f32_e32 v180, 1.0, v180
	v_add_f32_e32 v181, 1.0, v181
	v_rcp_f32_e32 v74, v74
	v_rcp_f32_e32 v75, v75
	v_rcp_f32_e32 v180, v180
	v_rcp_f32_e32 v181, v181
	v_mul_f32_e32 v74, v74, v178
	v_mul_f32_e32 v75, v75, v172
	v_mul_f32_e32 v180, v180, v179
	v_mul_f32_e32 v181, v181, v176
	v_mul_f32_e32 v74, v74, v180
	v_mul_f32_e32 v75, v75, v181
	v_lshlrev_b32_e32 v178, 16, v173
	v_and_b32_e32 v173, 0xffff0000, v173
	v_lshlrev_b32_e32 v179, 16, v177
	v_and_b32_e32 v177, 0xffff0000, v177
	v_mul_f32_e32 v76, 0xbfb8aa3b, v76
	v_mul_f32_e32 v77, 0xbfb8aa3b, v77
	v_mul_f32_e32 v180, 0xbfb8aa3b, v179
	v_mul_f32_e32 v181, 0xbfb8aa3b, v177
	v_exp_f32_e32 v76, v76
	v_exp_f32_e32 v77, v77
	v_exp_f32_e32 v180, v180
	v_exp_f32_e32 v181, v181
	v_add_f32_e32 v76, 1.0, v76
	v_add_f32_e32 v77, 1.0, v77
	v_add_f32_e32 v180, 1.0, v180
	v_add_f32_e32 v181, 1.0, v181
	v_rcp_f32_e32 v76, v76
	v_rcp_f32_e32 v77, v77
	v_rcp_f32_e32 v180, v180
	v_rcp_f32_e32 v181, v181
	v_mul_f32_e32 v76, v76, v178
	v_mul_f32_e32 v77, v77, v173
	v_mul_f32_e32 v180, v180, v179
	v_mul_f32_e32 v181, v181, v177
	v_mul_f32_e32 v76, v76, v180
	v_mul_f32_e32 v77, v77, v181
	v_cvt_pk_bf16_f32 v78, v78, v79
	v_cvt_pk_bf16_f32 v79, v80, v81
	v_cvt_pk_bf16_f32 v80, v74, v75
	v_cvt_pk_bf16_f32 v81, v76, v77
	global_store_dwordx4 v[146:147], v[78:81], off
	global_load_dwordx4 v[170:173], v[142:143], off offset:256
	global_load_dwordx4 v[174:177], v[144:145], off offset:256
	s_waitcnt vmcnt(6)
	v_lshlrev_b32_e32 v178, 16, v154
	v_and_b32_e32 v154, 0xffff0000, v154
	v_lshlrev_b32_e32 v179, 16, v158
	v_and_b32_e32 v158, 0xffff0000, v158
	v_mul_f32_e32 v70, 0xbfb8aa3b, v70
	v_mul_f32_e32 v71, 0xbfb8aa3b, v71
	v_mul_f32_e32 v180, 0xbfb8aa3b, v179
	v_mul_f32_e32 v181, 0xbfb8aa3b, v158
	v_exp_f32_e32 v70, v70
	v_exp_f32_e32 v71, v71
	v_exp_f32_e32 v180, v180
	v_exp_f32_e32 v181, v181
	v_add_f32_e32 v70, 1.0, v70
	v_add_f32_e32 v71, 1.0, v71
	v_add_f32_e32 v180, 1.0, v180
	v_add_f32_e32 v181, 1.0, v181
	v_rcp_f32_e32 v70, v70
	v_rcp_f32_e32 v71, v71
	v_rcp_f32_e32 v180, v180
	v_rcp_f32_e32 v181, v181
	v_mul_f32_e32 v70, v70, v178
	v_mul_f32_e32 v71, v71, v154
	v_mul_f32_e32 v180, v180, v179
	v_mul_f32_e32 v181, v181, v158
	v_mul_f32_e32 v70, v70, v180
	v_mul_f32_e32 v71, v71, v181
	v_lshlrev_b32_e32 v178, 16, v155
	v_and_b32_e32 v155, 0xffff0000, v155
	v_lshlrev_b32_e32 v179, 16, v159
	v_and_b32_e32 v159, 0xffff0000, v159
	v_mul_f32_e32 v72, 0xbfb8aa3b, v72
	v_mul_f32_e32 v73, 0xbfb8aa3b, v73
	v_mul_f32_e32 v180, 0xbfb8aa3b, v179
	v_mul_f32_e32 v181, 0xbfb8aa3b, v159
	v_exp_f32_e32 v72, v72
	v_exp_f32_e32 v73, v73
	v_exp_f32_e32 v180, v180
	v_exp_f32_e32 v181, v181
	v_add_f32_e32 v72, 1.0, v72
	v_add_f32_e32 v73, 1.0, v73
	v_add_f32_e32 v180, 1.0, v180
	v_add_f32_e32 v181, 1.0, v181
	v_rcp_f32_e32 v72, v72
	v_rcp_f32_e32 v73, v73
	v_rcp_f32_e32 v180, v180
	v_rcp_f32_e32 v181, v181
	v_mul_f32_e32 v72, v72, v178
	v_mul_f32_e32 v73, v73, v155
	v_mul_f32_e32 v180, v180, v179
	v_mul_f32_e32 v181, v181, v159
	v_mul_f32_e32 v72, v72, v180
	v_mul_f32_e32 v73, v73, v181
	v_lshlrev_b32_e32 v178, 16, v156
	v_and_b32_e32 v156, 0xffff0000, v156
	v_lshlrev_b32_e32 v179, 16, v160
	v_and_b32_e32 v160, 0xffff0000, v160
	v_mul_f32_e32 v66, 0xbfb8aa3b, v66
	v_mul_f32_e32 v67, 0xbfb8aa3b, v67
	v_mul_f32_e32 v180, 0xbfb8aa3b, v179
	v_mul_f32_e32 v181, 0xbfb8aa3b, v160
	v_exp_f32_e32 v66, v66
	v_exp_f32_e32 v67, v67
	v_exp_f32_e32 v180, v180
	v_exp_f32_e32 v181, v181
	v_add_f32_e32 v66, 1.0, v66
	v_add_f32_e32 v67, 1.0, v67
	v_add_f32_e32 v180, 1.0, v180
	v_add_f32_e32 v181, 1.0, v181
	v_rcp_f32_e32 v66, v66
	v_rcp_f32_e32 v67, v67
	v_rcp_f32_e32 v180, v180
	v_rcp_f32_e32 v181, v181
	v_mul_f32_e32 v66, v66, v178
	v_mul_f32_e32 v67, v67, v156
	v_mul_f32_e32 v180, v180, v179
	v_mul_f32_e32 v181, v181, v160
	v_mul_f32_e32 v66, v66, v180
	v_mul_f32_e32 v67, v67, v181
	v_lshlrev_b32_e32 v178, 16, v157
	v_and_b32_e32 v157, 0xffff0000, v157
	v_lshlrev_b32_e32 v179, 16, v161
	v_and_b32_e32 v161, 0xffff0000, v161
	v_mul_f32_e32 v68, 0xbfb8aa3b, v68
	v_mul_f32_e32 v69, 0xbfb8aa3b, v69
	v_mul_f32_e32 v180, 0xbfb8aa3b, v179
	v_mul_f32_e32 v181, 0xbfb8aa3b, v161
	v_exp_f32_e32 v68, v68
	v_exp_f32_e32 v69, v69
	v_exp_f32_e32 v180, v180
	v_exp_f32_e32 v181, v181
	v_add_f32_e32 v68, 1.0, v68
	v_add_f32_e32 v69, 1.0, v69
	v_add_f32_e32 v180, 1.0, v180
	v_add_f32_e32 v181, 1.0, v181
	v_rcp_f32_e32 v68, v68
	v_rcp_f32_e32 v69, v69
	v_rcp_f32_e32 v180, v180
	v_rcp_f32_e32 v181, v181
	v_mul_f32_e32 v68, v68, v178
	v_mul_f32_e32 v69, v69, v157
	v_mul_f32_e32 v180, v180, v179
	v_mul_f32_e32 v181, v181, v161
	v_mul_f32_e32 v68, v68, v180
	v_mul_f32_e32 v69, v69, v181
	v_cvt_pk_bf16_f32 v70, v70, v71
	v_cvt_pk_bf16_f32 v71, v72, v73
	v_cvt_pk_bf16_f32 v72, v66, v67
	v_cvt_pk_bf16_f32 v73, v68, v69
	global_store_dwordx4 v[146:147], v[70:73], off offset:256
	s_mov_b64 s[58:59], 0xa0000
	v_lshl_add_u64 v[146:147], v[146:147], 0, s[58:59]
	s_mov_b64 s[58:59], 0x8000
	v_lshl_add_u64 v[142:143], v[142:143], 0, s[58:59]
	s_mov_b64 s[58:59], 0x4000
	v_lshl_add_u64 v[144:145], v[144:145], 0, s[58:59]
	global_load_dwordx4 v[154:157], v[142:143], off
	global_load_dwordx4 v[158:161], v[144:145], off
	s_waitcnt vmcnt(6)
	v_lshlrev_b32_e32 v178, 16, v162
	v_and_b32_e32 v162, 0xffff0000, v162
	v_lshlrev_b32_e32 v179, 16, v166
	v_and_b32_e32 v166, 0xffff0000, v166
	v_mul_f32_e32 v62, 0xbfb8aa3b, v62
	v_mul_f32_e32 v63, 0xbfb8aa3b, v63
	v_mul_f32_e32 v180, 0xbfb8aa3b, v179
	v_mul_f32_e32 v181, 0xbfb8aa3b, v166
	v_exp_f32_e32 v62, v62
	v_exp_f32_e32 v63, v63
	v_exp_f32_e32 v180, v180
	v_exp_f32_e32 v181, v181
	v_add_f32_e32 v62, 1.0, v62
	v_add_f32_e32 v63, 1.0, v63
	v_add_f32_e32 v180, 1.0, v180
	v_add_f32_e32 v181, 1.0, v181
	v_rcp_f32_e32 v62, v62
	v_rcp_f32_e32 v63, v63
	v_rcp_f32_e32 v180, v180
	v_rcp_f32_e32 v181, v181
	v_mul_f32_e32 v62, v62, v178
	v_mul_f32_e32 v63, v63, v162
	v_mul_f32_e32 v180, v180, v179
	v_mul_f32_e32 v181, v181, v166
	v_mul_f32_e32 v62, v62, v180
	v_mul_f32_e32 v63, v63, v181
	v_lshlrev_b32_e32 v178, 16, v163
	v_and_b32_e32 v163, 0xffff0000, v163
	v_lshlrev_b32_e32 v179, 16, v167
	v_and_b32_e32 v167, 0xffff0000, v167
	v_mul_f32_e32 v64, 0xbfb8aa3b, v64
	v_mul_f32_e32 v65, 0xbfb8aa3b, v65
	v_mul_f32_e32 v180, 0xbfb8aa3b, v179
	v_mul_f32_e32 v181, 0xbfb8aa3b, v167
	v_exp_f32_e32 v64, v64
	v_exp_f32_e32 v65, v65
	v_exp_f32_e32 v180, v180
	v_exp_f32_e32 v181, v181
	v_add_f32_e32 v64, 1.0, v64
	v_add_f32_e32 v65, 1.0, v65
	v_add_f32_e32 v180, 1.0, v180
	v_add_f32_e32 v181, 1.0, v181
	v_rcp_f32_e32 v64, v64
	v_rcp_f32_e32 v65, v65
	v_rcp_f32_e32 v180, v180
	v_rcp_f32_e32 v181, v181
	v_mul_f32_e32 v64, v64, v178
	v_mul_f32_e32 v65, v65, v163
	v_mul_f32_e32 v180, v180, v179
	v_mul_f32_e32 v181, v181, v167
	v_mul_f32_e32 v64, v64, v180
	v_mul_f32_e32 v65, v65, v181
	v_lshlrev_b32_e32 v178, 16, v164
	v_and_b32_e32 v164, 0xffff0000, v164
	v_lshlrev_b32_e32 v179, 16, v168
	v_and_b32_e32 v168, 0xffff0000, v168
	v_mul_f32_e32 v58, 0xbfb8aa3b, v58
	v_mul_f32_e32 v59, 0xbfb8aa3b, v59
	v_mul_f32_e32 v180, 0xbfb8aa3b, v179
	v_mul_f32_e32 v181, 0xbfb8aa3b, v168
	v_exp_f32_e32 v58, v58
	v_exp_f32_e32 v59, v59
	v_exp_f32_e32 v180, v180
	v_exp_f32_e32 v181, v181
	v_add_f32_e32 v58, 1.0, v58
	v_add_f32_e32 v59, 1.0, v59
	v_add_f32_e32 v180, 1.0, v180
	v_add_f32_e32 v181, 1.0, v181
	v_rcp_f32_e32 v58, v58
	v_rcp_f32_e32 v59, v59
	v_rcp_f32_e32 v180, v180
	v_rcp_f32_e32 v181, v181
	v_mul_f32_e32 v58, v58, v178
	v_mul_f32_e32 v59, v59, v164
	v_mul_f32_e32 v180, v180, v179
	v_mul_f32_e32 v181, v181, v168
	v_mul_f32_e32 v58, v58, v180
	v_mul_f32_e32 v59, v59, v181
	v_lshlrev_b32_e32 v178, 16, v165
	v_and_b32_e32 v165, 0xffff0000, v165
	v_lshlrev_b32_e32 v179, 16, v169
	v_and_b32_e32 v169, 0xffff0000, v169
	v_mul_f32_e32 v60, 0xbfb8aa3b, v60
	v_mul_f32_e32 v61, 0xbfb8aa3b, v61
	v_mul_f32_e32 v180, 0xbfb8aa3b, v179
	v_mul_f32_e32 v181, 0xbfb8aa3b, v169
	v_exp_f32_e32 v60, v60
	v_exp_f32_e32 v61, v61
	v_exp_f32_e32 v180, v180
	v_exp_f32_e32 v181, v181
	v_add_f32_e32 v60, 1.0, v60
	v_add_f32_e32 v61, 1.0, v61
	v_add_f32_e32 v180, 1.0, v180
	v_add_f32_e32 v181, 1.0, v181
	v_rcp_f32_e32 v60, v60
	v_rcp_f32_e32 v61, v61
	v_rcp_f32_e32 v180, v180
	v_rcp_f32_e32 v181, v181
	v_mul_f32_e32 v60, v60, v178
	v_mul_f32_e32 v61, v61, v165
	v_mul_f32_e32 v180, v180, v179
	v_mul_f32_e32 v181, v181, v169
	v_mul_f32_e32 v60, v60, v180
	v_mul_f32_e32 v61, v61, v181
	v_cvt_pk_bf16_f32 v62, v62, v63
	v_cvt_pk_bf16_f32 v63, v64, v65
	v_cvt_pk_bf16_f32 v64, v58, v59
	v_cvt_pk_bf16_f32 v65, v60, v61
	global_store_dwordx4 v[146:147], v[62:65], off
	global_load_dwordx4 v[162:165], v[142:143], off offset:256
	global_load_dwordx4 v[166:169], v[144:145], off offset:256
	s_waitcnt vmcnt(6)
	v_lshlrev_b32_e32 v178, 16, v170
	v_and_b32_e32 v170, 0xffff0000, v170
	v_lshlrev_b32_e32 v179, 16, v174
	v_and_b32_e32 v174, 0xffff0000, v174
	v_mul_f32_e32 v54, 0xbfb8aa3b, v54
	v_mul_f32_e32 v55, 0xbfb8aa3b, v55
	v_mul_f32_e32 v180, 0xbfb8aa3b, v179
	v_mul_f32_e32 v181, 0xbfb8aa3b, v174
	v_exp_f32_e32 v54, v54
	v_exp_f32_e32 v55, v55
	v_exp_f32_e32 v180, v180
	v_exp_f32_e32 v181, v181
	v_add_f32_e32 v54, 1.0, v54
	v_add_f32_e32 v55, 1.0, v55
	v_add_f32_e32 v180, 1.0, v180
	v_add_f32_e32 v181, 1.0, v181
	v_rcp_f32_e32 v54, v54
	v_rcp_f32_e32 v55, v55
	v_rcp_f32_e32 v180, v180
	v_rcp_f32_e32 v181, v181
	v_mul_f32_e32 v54, v54, v178
	v_mul_f32_e32 v55, v55, v170
	v_mul_f32_e32 v180, v180, v179
	v_mul_f32_e32 v181, v181, v174
	v_mul_f32_e32 v54, v54, v180
	v_mul_f32_e32 v55, v55, v181
	v_lshlrev_b32_e32 v178, 16, v171
	v_and_b32_e32 v171, 0xffff0000, v171
	v_lshlrev_b32_e32 v179, 16, v175
	v_and_b32_e32 v175, 0xffff0000, v175
	v_mul_f32_e32 v56, 0xbfb8aa3b, v56
	v_mul_f32_e32 v57, 0xbfb8aa3b, v57
	v_mul_f32_e32 v180, 0xbfb8aa3b, v179
	v_mul_f32_e32 v181, 0xbfb8aa3b, v175
	v_exp_f32_e32 v56, v56
	v_exp_f32_e32 v57, v57
	v_exp_f32_e32 v180, v180
	v_exp_f32_e32 v181, v181
	v_add_f32_e32 v56, 1.0, v56
	v_add_f32_e32 v57, 1.0, v57
	v_add_f32_e32 v180, 1.0, v180
	v_add_f32_e32 v181, 1.0, v181
	v_rcp_f32_e32 v56, v56
	v_rcp_f32_e32 v57, v57
	v_rcp_f32_e32 v180, v180
	v_rcp_f32_e32 v181, v181
	v_mul_f32_e32 v56, v56, v178
	v_mul_f32_e32 v57, v57, v171
	v_mul_f32_e32 v180, v180, v179
	v_mul_f32_e32 v181, v181, v175
	v_mul_f32_e32 v56, v56, v180
	v_mul_f32_e32 v57, v57, v181
	v_lshlrev_b32_e32 v178, 16, v172
	v_and_b32_e32 v172, 0xffff0000, v172
	v_lshlrev_b32_e32 v179, 16, v176
	v_and_b32_e32 v176, 0xffff0000, v176
	v_mul_f32_e32 v50, 0xbfb8aa3b, v50
	v_mul_f32_e32 v51, 0xbfb8aa3b, v51
	v_mul_f32_e32 v180, 0xbfb8aa3b, v179
	v_mul_f32_e32 v181, 0xbfb8aa3b, v176
	v_exp_f32_e32 v50, v50
	v_exp_f32_e32 v51, v51
	v_exp_f32_e32 v180, v180
	v_exp_f32_e32 v181, v181
	v_add_f32_e32 v50, 1.0, v50
	v_add_f32_e32 v51, 1.0, v51
	v_add_f32_e32 v180, 1.0, v180
	v_add_f32_e32 v181, 1.0, v181
	v_rcp_f32_e32 v50, v50
	v_rcp_f32_e32 v51, v51
	v_rcp_f32_e32 v180, v180
	v_rcp_f32_e32 v181, v181
	v_mul_f32_e32 v50, v50, v178
	v_mul_f32_e32 v51, v51, v172
	v_mul_f32_e32 v180, v180, v179
	v_mul_f32_e32 v181, v181, v176
	v_mul_f32_e32 v50, v50, v180
	v_mul_f32_e32 v51, v51, v181
	v_lshlrev_b32_e32 v178, 16, v173
	v_and_b32_e32 v173, 0xffff0000, v173
	v_lshlrev_b32_e32 v179, 16, v177
	v_and_b32_e32 v177, 0xffff0000, v177
	v_mul_f32_e32 v52, 0xbfb8aa3b, v52
	v_mul_f32_e32 v53, 0xbfb8aa3b, v53
	v_mul_f32_e32 v180, 0xbfb8aa3b, v179
	v_mul_f32_e32 v181, 0xbfb8aa3b, v177
	v_exp_f32_e32 v52, v52
	v_exp_f32_e32 v53, v53
	v_exp_f32_e32 v180, v180
	v_exp_f32_e32 v181, v181
	v_add_f32_e32 v52, 1.0, v52
	v_add_f32_e32 v53, 1.0, v53
	v_add_f32_e32 v180, 1.0, v180
	v_add_f32_e32 v181, 1.0, v181
	v_rcp_f32_e32 v52, v52
	v_rcp_f32_e32 v53, v53
	v_rcp_f32_e32 v180, v180
	v_rcp_f32_e32 v181, v181
	v_mul_f32_e32 v52, v52, v178
	v_mul_f32_e32 v53, v53, v173
	v_mul_f32_e32 v180, v180, v179
	v_mul_f32_e32 v181, v181, v177
	v_mul_f32_e32 v52, v52, v180
	v_mul_f32_e32 v53, v53, v181
	v_cvt_pk_bf16_f32 v54, v54, v55
	v_cvt_pk_bf16_f32 v55, v56, v57
	v_cvt_pk_bf16_f32 v56, v50, v51
	v_cvt_pk_bf16_f32 v57, v52, v53
	global_store_dwordx4 v[146:147], v[54:57], off offset:256
	s_mov_b64 s[58:59], 0x20000
	v_lshl_add_u64 v[146:147], v[146:147], 0, s[58:59]
	s_mov_b64 s[58:59], 0x8000
	v_lshl_add_u64 v[142:143], v[142:143], 0, s[58:59]
	s_mov_b64 s[58:59], 0x4000
	v_lshl_add_u64 v[144:145], v[144:145], 0, s[58:59]
	global_load_dwordx4 v[170:173], v[142:143], off
	global_load_dwordx4 v[174:177], v[144:145], off
	s_waitcnt vmcnt(6)
	v_lshlrev_b32_e32 v178, 16, v154
	v_and_b32_e32 v154, 0xffff0000, v154
	v_lshlrev_b32_e32 v179, 16, v158
	v_and_b32_e32 v158, 0xffff0000, v158
	v_mul_f32_e32 v46, 0xbfb8aa3b, v46
	v_mul_f32_e32 v47, 0xbfb8aa3b, v47
	v_mul_f32_e32 v180, 0xbfb8aa3b, v179
	v_mul_f32_e32 v181, 0xbfb8aa3b, v158
	v_exp_f32_e32 v46, v46
	v_exp_f32_e32 v47, v47
	v_exp_f32_e32 v180, v180
	v_exp_f32_e32 v181, v181
	v_add_f32_e32 v46, 1.0, v46
	v_add_f32_e32 v47, 1.0, v47
	v_add_f32_e32 v180, 1.0, v180
	v_add_f32_e32 v181, 1.0, v181
	v_rcp_f32_e32 v46, v46
	v_rcp_f32_e32 v47, v47
	v_rcp_f32_e32 v180, v180
	v_rcp_f32_e32 v181, v181
	v_mul_f32_e32 v46, v46, v178
	v_mul_f32_e32 v47, v47, v154
	v_mul_f32_e32 v180, v180, v179
	v_mul_f32_e32 v181, v181, v158
	v_mul_f32_e32 v46, v46, v180
	v_mul_f32_e32 v47, v47, v181
	v_lshlrev_b32_e32 v178, 16, v155
	v_and_b32_e32 v155, 0xffff0000, v155
	v_lshlrev_b32_e32 v179, 16, v159
	v_and_b32_e32 v159, 0xffff0000, v159
	v_mul_f32_e32 v48, 0xbfb8aa3b, v48
	v_mul_f32_e32 v49, 0xbfb8aa3b, v49
	v_mul_f32_e32 v180, 0xbfb8aa3b, v179
	v_mul_f32_e32 v181, 0xbfb8aa3b, v159
	v_exp_f32_e32 v48, v48
	v_exp_f32_e32 v49, v49
	v_exp_f32_e32 v180, v180
	v_exp_f32_e32 v181, v181
	v_add_f32_e32 v48, 1.0, v48
	v_add_f32_e32 v49, 1.0, v49
	v_add_f32_e32 v180, 1.0, v180
	v_add_f32_e32 v181, 1.0, v181
	v_rcp_f32_e32 v48, v48
	v_rcp_f32_e32 v49, v49
	v_rcp_f32_e32 v180, v180
	v_rcp_f32_e32 v181, v181
	v_mul_f32_e32 v48, v48, v178
	v_mul_f32_e32 v49, v49, v155
	v_mul_f32_e32 v180, v180, v179
	v_mul_f32_e32 v181, v181, v159
	v_mul_f32_e32 v48, v48, v180
	v_mul_f32_e32 v49, v49, v181
	v_lshlrev_b32_e32 v178, 16, v156
	v_and_b32_e32 v156, 0xffff0000, v156
	v_lshlrev_b32_e32 v179, 16, v160
	v_and_b32_e32 v160, 0xffff0000, v160
	v_mul_f32_e32 v42, 0xbfb8aa3b, v42
	v_mul_f32_e32 v43, 0xbfb8aa3b, v43
	v_mul_f32_e32 v180, 0xbfb8aa3b, v179
	v_mul_f32_e32 v181, 0xbfb8aa3b, v160
	v_exp_f32_e32 v42, v42
	v_exp_f32_e32 v43, v43
	v_exp_f32_e32 v180, v180
	v_exp_f32_e32 v181, v181
	v_add_f32_e32 v42, 1.0, v42
	v_add_f32_e32 v43, 1.0, v43
	v_add_f32_e32 v180, 1.0, v180
	v_add_f32_e32 v181, 1.0, v181
	v_rcp_f32_e32 v42, v42
	v_rcp_f32_e32 v43, v43
	v_rcp_f32_e32 v180, v180
	v_rcp_f32_e32 v181, v181
	v_mul_f32_e32 v42, v42, v178
	v_mul_f32_e32 v43, v43, v156
	v_mul_f32_e32 v180, v180, v179
	v_mul_f32_e32 v181, v181, v160
	v_mul_f32_e32 v42, v42, v180
	v_mul_f32_e32 v43, v43, v181
	v_lshlrev_b32_e32 v178, 16, v157
	v_and_b32_e32 v157, 0xffff0000, v157
	v_lshlrev_b32_e32 v179, 16, v161
	v_and_b32_e32 v161, 0xffff0000, v161
	v_mul_f32_e32 v44, 0xbfb8aa3b, v44
	v_mul_f32_e32 v45, 0xbfb8aa3b, v45
	v_mul_f32_e32 v180, 0xbfb8aa3b, v179
	v_mul_f32_e32 v181, 0xbfb8aa3b, v161
	v_exp_f32_e32 v44, v44
	v_exp_f32_e32 v45, v45
	v_exp_f32_e32 v180, v180
	v_exp_f32_e32 v181, v181
	v_add_f32_e32 v44, 1.0, v44
	v_add_f32_e32 v45, 1.0, v45
	v_add_f32_e32 v180, 1.0, v180
	v_add_f32_e32 v181, 1.0, v181
	v_rcp_f32_e32 v44, v44
	v_rcp_f32_e32 v45, v45
	v_rcp_f32_e32 v180, v180
	v_rcp_f32_e32 v181, v181
	v_mul_f32_e32 v44, v44, v178
	v_mul_f32_e32 v45, v45, v157
	v_mul_f32_e32 v180, v180, v179
	v_mul_f32_e32 v181, v181, v161
	v_mul_f32_e32 v44, v44, v180
	v_mul_f32_e32 v45, v45, v181
	v_cvt_pk_bf16_f32 v46, v46, v47
	v_cvt_pk_bf16_f32 v47, v48, v49
	v_cvt_pk_bf16_f32 v48, v42, v43
	v_cvt_pk_bf16_f32 v49, v44, v45
	global_store_dwordx4 v[146:147], v[46:49], off
	global_load_dwordx4 v[154:157], v[142:143], off offset:256
	global_load_dwordx4 v[158:161], v[144:145], off offset:256
	s_waitcnt vmcnt(6)
	v_lshlrev_b32_e32 v178, 16, v162
	v_and_b32_e32 v162, 0xffff0000, v162
	v_lshlrev_b32_e32 v179, 16, v166
	v_and_b32_e32 v166, 0xffff0000, v166
	v_mul_f32_e32 v38, 0xbfb8aa3b, v38
	v_mul_f32_e32 v39, 0xbfb8aa3b, v39
	v_mul_f32_e32 v180, 0xbfb8aa3b, v179
	v_mul_f32_e32 v181, 0xbfb8aa3b, v166
	v_exp_f32_e32 v38, v38
	v_exp_f32_e32 v39, v39
	v_exp_f32_e32 v180, v180
	v_exp_f32_e32 v181, v181
	v_add_f32_e32 v38, 1.0, v38
	v_add_f32_e32 v39, 1.0, v39
	v_add_f32_e32 v180, 1.0, v180
	v_add_f32_e32 v181, 1.0, v181
	v_rcp_f32_e32 v38, v38
	v_rcp_f32_e32 v39, v39
	v_rcp_f32_e32 v180, v180
	v_rcp_f32_e32 v181, v181
	v_mul_f32_e32 v38, v38, v178
	v_mul_f32_e32 v39, v39, v162
	v_mul_f32_e32 v180, v180, v179
	v_mul_f32_e32 v181, v181, v166
	v_mul_f32_e32 v38, v38, v180
	v_mul_f32_e32 v39, v39, v181
	v_lshlrev_b32_e32 v178, 16, v163
	v_and_b32_e32 v163, 0xffff0000, v163
	v_lshlrev_b32_e32 v179, 16, v167
	v_and_b32_e32 v167, 0xffff0000, v167
	v_mul_f32_e32 v40, 0xbfb8aa3b, v40
	v_mul_f32_e32 v41, 0xbfb8aa3b, v41
	v_mul_f32_e32 v180, 0xbfb8aa3b, v179
	v_mul_f32_e32 v181, 0xbfb8aa3b, v167
	v_exp_f32_e32 v40, v40
	v_exp_f32_e32 v41, v41
	v_exp_f32_e32 v180, v180
	v_exp_f32_e32 v181, v181
	v_add_f32_e32 v40, 1.0, v40
	v_add_f32_e32 v41, 1.0, v41
	v_add_f32_e32 v180, 1.0, v180
	v_add_f32_e32 v181, 1.0, v181
	v_rcp_f32_e32 v40, v40
	v_rcp_f32_e32 v41, v41
	v_rcp_f32_e32 v180, v180
	v_rcp_f32_e32 v181, v181
	v_mul_f32_e32 v40, v40, v178
	v_mul_f32_e32 v41, v41, v163
	v_mul_f32_e32 v180, v180, v179
	v_mul_f32_e32 v181, v181, v167
	v_mul_f32_e32 v40, v40, v180
	v_mul_f32_e32 v41, v41, v181
	v_lshlrev_b32_e32 v178, 16, v164
	v_and_b32_e32 v164, 0xffff0000, v164
	v_lshlrev_b32_e32 v179, 16, v168
	v_and_b32_e32 v168, 0xffff0000, v168
	v_mul_f32_e32 v34, 0xbfb8aa3b, v34
	v_mul_f32_e32 v35, 0xbfb8aa3b, v35
	v_mul_f32_e32 v180, 0xbfb8aa3b, v179
	v_mul_f32_e32 v181, 0xbfb8aa3b, v168
	v_exp_f32_e32 v34, v34
	v_exp_f32_e32 v35, v35
	v_exp_f32_e32 v180, v180
	v_exp_f32_e32 v181, v181
	v_add_f32_e32 v34, 1.0, v34
	v_add_f32_e32 v35, 1.0, v35
	v_add_f32_e32 v180, 1.0, v180
	v_add_f32_e32 v181, 1.0, v181
	v_rcp_f32_e32 v34, v34
	v_rcp_f32_e32 v35, v35
	v_rcp_f32_e32 v180, v180
	v_rcp_f32_e32 v181, v181
	v_mul_f32_e32 v34, v34, v178
	v_mul_f32_e32 v35, v35, v164
	v_mul_f32_e32 v180, v180, v179
	v_mul_f32_e32 v181, v181, v168
	v_mul_f32_e32 v34, v34, v180
	v_mul_f32_e32 v35, v35, v181
	v_lshlrev_b32_e32 v178, 16, v165
	v_and_b32_e32 v165, 0xffff0000, v165
	v_lshlrev_b32_e32 v179, 16, v169
	v_and_b32_e32 v169, 0xffff0000, v169
	v_mul_f32_e32 v36, 0xbfb8aa3b, v36
	v_mul_f32_e32 v37, 0xbfb8aa3b, v37
	v_mul_f32_e32 v180, 0xbfb8aa3b, v179
	v_mul_f32_e32 v181, 0xbfb8aa3b, v169
	v_exp_f32_e32 v36, v36
	v_exp_f32_e32 v37, v37
	v_exp_f32_e32 v180, v180
	v_exp_f32_e32 v181, v181
	v_add_f32_e32 v36, 1.0, v36
	v_add_f32_e32 v37, 1.0, v37
	v_add_f32_e32 v180, 1.0, v180
	v_add_f32_e32 v181, 1.0, v181
	v_rcp_f32_e32 v36, v36
	v_rcp_f32_e32 v37, v37
	v_rcp_f32_e32 v180, v180
	v_rcp_f32_e32 v181, v181
	v_mul_f32_e32 v36, v36, v178
	v_mul_f32_e32 v37, v37, v165
	v_mul_f32_e32 v180, v180, v179
	v_mul_f32_e32 v181, v181, v169
	v_mul_f32_e32 v36, v36, v180
	v_mul_f32_e32 v37, v37, v181
	v_cvt_pk_bf16_f32 v38, v38, v39
	v_cvt_pk_bf16_f32 v39, v40, v41
	v_cvt_pk_bf16_f32 v40, v34, v35
	v_cvt_pk_bf16_f32 v41, v36, v37
	global_store_dwordx4 v[146:147], v[38:41], off offset:256
	s_mov_b64 s[58:59], 0x20000
	v_lshl_add_u64 v[146:147], v[146:147], 0, s[58:59]
	s_mov_b64 s[58:59], 0x8000
	v_lshl_add_u64 v[142:143], v[142:143], 0, s[58:59]
	s_mov_b64 s[58:59], 0x4000
	v_lshl_add_u64 v[144:145], v[144:145], 0, s[58:59]
	global_load_dwordx4 v[162:165], v[142:143], off
	global_load_dwordx4 v[166:169], v[144:145], off
	s_waitcnt vmcnt(6)
	v_lshlrev_b32_e32 v178, 16, v170
	v_and_b32_e32 v170, 0xffff0000, v170
	v_lshlrev_b32_e32 v179, 16, v174
	v_and_b32_e32 v174, 0xffff0000, v174
	v_mul_f32_e32 v30, 0xbfb8aa3b, v30
	v_mul_f32_e32 v31, 0xbfb8aa3b, v31
	v_mul_f32_e32 v180, 0xbfb8aa3b, v179
	v_mul_f32_e32 v181, 0xbfb8aa3b, v174
	v_exp_f32_e32 v30, v30
	v_exp_f32_e32 v31, v31
	v_exp_f32_e32 v180, v180
	v_exp_f32_e32 v181, v181
	v_add_f32_e32 v30, 1.0, v30
	v_add_f32_e32 v31, 1.0, v31
	v_add_f32_e32 v180, 1.0, v180
	v_add_f32_e32 v181, 1.0, v181
	v_rcp_f32_e32 v30, v30
	v_rcp_f32_e32 v31, v31
	v_rcp_f32_e32 v180, v180
	v_rcp_f32_e32 v181, v181
	v_mul_f32_e32 v30, v30, v178
	v_mul_f32_e32 v31, v31, v170
	v_mul_f32_e32 v180, v180, v179
	v_mul_f32_e32 v181, v181, v174
	v_mul_f32_e32 v30, v30, v180
	v_mul_f32_e32 v31, v31, v181
	v_lshlrev_b32_e32 v178, 16, v171
	v_and_b32_e32 v171, 0xffff0000, v171
	v_lshlrev_b32_e32 v179, 16, v175
	v_and_b32_e32 v175, 0xffff0000, v175
	v_mul_f32_e32 v32, 0xbfb8aa3b, v32
	v_mul_f32_e32 v33, 0xbfb8aa3b, v33
	v_mul_f32_e32 v180, 0xbfb8aa3b, v179
	v_mul_f32_e32 v181, 0xbfb8aa3b, v175
	v_exp_f32_e32 v32, v32
	v_exp_f32_e32 v33, v33
	v_exp_f32_e32 v180, v180
	v_exp_f32_e32 v181, v181
	v_add_f32_e32 v32, 1.0, v32
	v_add_f32_e32 v33, 1.0, v33
	v_add_f32_e32 v180, 1.0, v180
	v_add_f32_e32 v181, 1.0, v181
	v_rcp_f32_e32 v32, v32
	v_rcp_f32_e32 v33, v33
	v_rcp_f32_e32 v180, v180
	v_rcp_f32_e32 v181, v181
	v_mul_f32_e32 v32, v32, v178
	v_mul_f32_e32 v33, v33, v171
	v_mul_f32_e32 v180, v180, v179
	v_mul_f32_e32 v181, v181, v175
	v_mul_f32_e32 v32, v32, v180
	v_mul_f32_e32 v33, v33, v181
	v_lshlrev_b32_e32 v178, 16, v172
	v_and_b32_e32 v172, 0xffff0000, v172
	v_lshlrev_b32_e32 v179, 16, v176
	v_and_b32_e32 v176, 0xffff0000, v176
	v_mul_f32_e32 v26, 0xbfb8aa3b, v26
	v_mul_f32_e32 v27, 0xbfb8aa3b, v27
	v_mul_f32_e32 v180, 0xbfb8aa3b, v179
	v_mul_f32_e32 v181, 0xbfb8aa3b, v176
	v_exp_f32_e32 v26, v26
	v_exp_f32_e32 v27, v27
	v_exp_f32_e32 v180, v180
	v_exp_f32_e32 v181, v181
	v_add_f32_e32 v26, 1.0, v26
	v_add_f32_e32 v27, 1.0, v27
	v_add_f32_e32 v180, 1.0, v180
	v_add_f32_e32 v181, 1.0, v181
	v_rcp_f32_e32 v26, v26
	v_rcp_f32_e32 v27, v27
	v_rcp_f32_e32 v180, v180
	v_rcp_f32_e32 v181, v181
	v_mul_f32_e32 v26, v26, v178
	v_mul_f32_e32 v27, v27, v172
	v_mul_f32_e32 v180, v180, v179
	v_mul_f32_e32 v181, v181, v176
	v_mul_f32_e32 v26, v26, v180
	v_mul_f32_e32 v27, v27, v181
	v_lshlrev_b32_e32 v178, 16, v173
	v_and_b32_e32 v173, 0xffff0000, v173
	v_lshlrev_b32_e32 v179, 16, v177
	v_and_b32_e32 v177, 0xffff0000, v177
	v_mul_f32_e32 v28, 0xbfb8aa3b, v28
	v_mul_f32_e32 v29, 0xbfb8aa3b, v29
	v_mul_f32_e32 v180, 0xbfb8aa3b, v179
	v_mul_f32_e32 v181, 0xbfb8aa3b, v177
	v_exp_f32_e32 v28, v28
	v_exp_f32_e32 v29, v29
	v_exp_f32_e32 v180, v180
	v_exp_f32_e32 v181, v181
	v_add_f32_e32 v28, 1.0, v28
	v_add_f32_e32 v29, 1.0, v29
	v_add_f32_e32 v180, 1.0, v180
	v_add_f32_e32 v181, 1.0, v181
	v_rcp_f32_e32 v28, v28
	v_rcp_f32_e32 v29, v29
	v_rcp_f32_e32 v180, v180
	v_rcp_f32_e32 v181, v181
	v_mul_f32_e32 v28, v28, v178
	v_mul_f32_e32 v29, v29, v173
	v_mul_f32_e32 v180, v180, v179
	v_mul_f32_e32 v181, v181, v177
	v_mul_f32_e32 v28, v28, v180
	v_mul_f32_e32 v29, v29, v181
	v_cvt_pk_bf16_f32 v30, v30, v31
	v_cvt_pk_bf16_f32 v31, v32, v33
	v_cvt_pk_bf16_f32 v32, v26, v27
	v_cvt_pk_bf16_f32 v33, v28, v29
	global_store_dwordx4 v[146:147], v[30:33], off
	global_load_dwordx4 v[170:173], v[142:143], off offset:256
	global_load_dwordx4 v[174:177], v[144:145], off offset:256
	s_waitcnt vmcnt(6)
	v_lshlrev_b32_e32 v178, 16, v154
	v_and_b32_e32 v154, 0xffff0000, v154
	v_lshlrev_b32_e32 v179, 16, v158
	v_and_b32_e32 v158, 0xffff0000, v158
	v_mul_f32_e32 v22, 0xbfb8aa3b, v22
	v_mul_f32_e32 v23, 0xbfb8aa3b, v23
	v_mul_f32_e32 v180, 0xbfb8aa3b, v179
	v_mul_f32_e32 v181, 0xbfb8aa3b, v158
	v_exp_f32_e32 v22, v22
	v_exp_f32_e32 v23, v23
	v_exp_f32_e32 v180, v180
	v_exp_f32_e32 v181, v181
	v_add_f32_e32 v22, 1.0, v22
	v_add_f32_e32 v23, 1.0, v23
	v_add_f32_e32 v180, 1.0, v180
	v_add_f32_e32 v181, 1.0, v181
	v_rcp_f32_e32 v22, v22
	v_rcp_f32_e32 v23, v23
	v_rcp_f32_e32 v180, v180
	v_rcp_f32_e32 v181, v181
	v_mul_f32_e32 v22, v22, v178
	v_mul_f32_e32 v23, v23, v154
	v_mul_f32_e32 v180, v180, v179
	v_mul_f32_e32 v181, v181, v158
	v_mul_f32_e32 v22, v22, v180
	v_mul_f32_e32 v23, v23, v181
	v_lshlrev_b32_e32 v178, 16, v155
	v_and_b32_e32 v155, 0xffff0000, v155
	v_lshlrev_b32_e32 v179, 16, v159
	v_and_b32_e32 v159, 0xffff0000, v159
	v_mul_f32_e32 v24, 0xbfb8aa3b, v24
	v_mul_f32_e32 v25, 0xbfb8aa3b, v25
	v_mul_f32_e32 v180, 0xbfb8aa3b, v179
	v_mul_f32_e32 v181, 0xbfb8aa3b, v159
	v_exp_f32_e32 v24, v24
	v_exp_f32_e32 v25, v25
	v_exp_f32_e32 v180, v180
	v_exp_f32_e32 v181, v181
	v_add_f32_e32 v24, 1.0, v24
	v_add_f32_e32 v25, 1.0, v25
	v_add_f32_e32 v180, 1.0, v180
	v_add_f32_e32 v181, 1.0, v181
	v_rcp_f32_e32 v24, v24
	v_rcp_f32_e32 v25, v25
	v_rcp_f32_e32 v180, v180
	v_rcp_f32_e32 v181, v181
	v_mul_f32_e32 v24, v24, v178
	v_mul_f32_e32 v25, v25, v155
	v_mul_f32_e32 v180, v180, v179
	v_mul_f32_e32 v181, v181, v159
	v_mul_f32_e32 v24, v24, v180
	v_mul_f32_e32 v25, v25, v181
	v_lshlrev_b32_e32 v178, 16, v156
	v_and_b32_e32 v156, 0xffff0000, v156
	v_lshlrev_b32_e32 v179, 16, v160
	v_and_b32_e32 v160, 0xffff0000, v160
	v_mul_f32_e32 v18, 0xbfb8aa3b, v18
	v_mul_f32_e32 v19, 0xbfb8aa3b, v19
	v_mul_f32_e32 v180, 0xbfb8aa3b, v179
	v_mul_f32_e32 v181, 0xbfb8aa3b, v160
	v_exp_f32_e32 v18, v18
	v_exp_f32_e32 v19, v19
	v_exp_f32_e32 v180, v180
	v_exp_f32_e32 v181, v181
	v_add_f32_e32 v18, 1.0, v18
	v_add_f32_e32 v19, 1.0, v19
	v_add_f32_e32 v180, 1.0, v180
	v_add_f32_e32 v181, 1.0, v181
	v_rcp_f32_e32 v18, v18
	v_rcp_f32_e32 v19, v19
	v_rcp_f32_e32 v180, v180
	v_rcp_f32_e32 v181, v181
	v_mul_f32_e32 v18, v18, v178
	v_mul_f32_e32 v19, v19, v156
	v_mul_f32_e32 v180, v180, v179
	v_mul_f32_e32 v181, v181, v160
	v_mul_f32_e32 v18, v18, v180
	v_mul_f32_e32 v19, v19, v181
	v_lshlrev_b32_e32 v178, 16, v157
	v_and_b32_e32 v157, 0xffff0000, v157
	v_lshlrev_b32_e32 v179, 16, v161
	v_and_b32_e32 v161, 0xffff0000, v161
	v_mul_f32_e32 v20, 0xbfb8aa3b, v20
	v_mul_f32_e32 v21, 0xbfb8aa3b, v21
	v_mul_f32_e32 v180, 0xbfb8aa3b, v179
	v_mul_f32_e32 v181, 0xbfb8aa3b, v161
	v_exp_f32_e32 v20, v20
	v_exp_f32_e32 v21, v21
	v_exp_f32_e32 v180, v180
	v_exp_f32_e32 v181, v181
	v_add_f32_e32 v20, 1.0, v20
	v_add_f32_e32 v21, 1.0, v21
	v_add_f32_e32 v180, 1.0, v180
	v_add_f32_e32 v181, 1.0, v181
	v_rcp_f32_e32 v20, v20
	v_rcp_f32_e32 v21, v21
	v_rcp_f32_e32 v180, v180
	v_rcp_f32_e32 v181, v181
	v_mul_f32_e32 v20, v20, v178
	v_mul_f32_e32 v21, v21, v157
	v_mul_f32_e32 v180, v180, v179
	v_mul_f32_e32 v181, v181, v161
	v_mul_f32_e32 v20, v20, v180
	v_mul_f32_e32 v21, v21, v181
	v_cvt_pk_bf16_f32 v22, v22, v23
	v_cvt_pk_bf16_f32 v23, v24, v25
	v_cvt_pk_bf16_f32 v24, v18, v19
	v_cvt_pk_bf16_f32 v25, v20, v21
	global_store_dwordx4 v[146:147], v[22:25], off offset:256
	s_mov_b64 s[58:59], 0x20000
	v_lshl_add_u64 v[146:147], v[146:147], 0, s[58:59]
	s_waitcnt vmcnt(4)
	v_lshlrev_b32_e32 v178, 16, v162
	v_and_b32_e32 v162, 0xffff0000, v162
	v_lshlrev_b32_e32 v179, 16, v166
	v_and_b32_e32 v166, 0xffff0000, v166
	v_mul_f32_e32 v14, 0xbfb8aa3b, v14
	v_mul_f32_e32 v15, 0xbfb8aa3b, v15
	v_mul_f32_e32 v180, 0xbfb8aa3b, v179
	v_mul_f32_e32 v181, 0xbfb8aa3b, v166
	v_exp_f32_e32 v14, v14
	v_exp_f32_e32 v15, v15
	v_exp_f32_e32 v180, v180
	v_exp_f32_e32 v181, v181
	v_add_f32_e32 v14, 1.0, v14
	v_add_f32_e32 v15, 1.0, v15
	v_add_f32_e32 v180, 1.0, v180
	v_add_f32_e32 v181, 1.0, v181
	v_rcp_f32_e32 v14, v14
	v_rcp_f32_e32 v15, v15
	v_rcp_f32_e32 v180, v180
	v_rcp_f32_e32 v181, v181
	v_mul_f32_e32 v14, v14, v178
	v_mul_f32_e32 v15, v15, v162
	v_mul_f32_e32 v180, v180, v179
	v_mul_f32_e32 v181, v181, v166
	v_mul_f32_e32 v14, v14, v180
	v_mul_f32_e32 v15, v15, v181
	v_lshlrev_b32_e32 v178, 16, v163
	v_and_b32_e32 v163, 0xffff0000, v163
	v_lshlrev_b32_e32 v179, 16, v167
	v_and_b32_e32 v167, 0xffff0000, v167
	v_mul_f32_e32 v16, 0xbfb8aa3b, v16
	v_mul_f32_e32 v17, 0xbfb8aa3b, v17
	v_mul_f32_e32 v180, 0xbfb8aa3b, v179
	v_mul_f32_e32 v181, 0xbfb8aa3b, v167
	v_exp_f32_e32 v16, v16
	v_exp_f32_e32 v17, v17
	v_exp_f32_e32 v180, v180
	v_exp_f32_e32 v181, v181
	v_add_f32_e32 v16, 1.0, v16
	v_add_f32_e32 v17, 1.0, v17
	v_add_f32_e32 v180, 1.0, v180
	v_add_f32_e32 v181, 1.0, v181
	v_rcp_f32_e32 v16, v16
	v_rcp_f32_e32 v17, v17
	v_rcp_f32_e32 v180, v180
	v_rcp_f32_e32 v181, v181
	v_mul_f32_e32 v16, v16, v178
	v_mul_f32_e32 v17, v17, v163
	v_mul_f32_e32 v180, v180, v179
	v_mul_f32_e32 v181, v181, v167
	v_mul_f32_e32 v16, v16, v180
	v_mul_f32_e32 v17, v17, v181
	v_lshlrev_b32_e32 v178, 16, v164
	v_and_b32_e32 v164, 0xffff0000, v164
	v_lshlrev_b32_e32 v179, 16, v168
	v_and_b32_e32 v168, 0xffff0000, v168
	v_mul_f32_e32 v10, 0xbfb8aa3b, v10
	v_mul_f32_e32 v11, 0xbfb8aa3b, v11
	v_mul_f32_e32 v180, 0xbfb8aa3b, v179
	v_mul_f32_e32 v181, 0xbfb8aa3b, v168
	v_exp_f32_e32 v10, v10
	v_exp_f32_e32 v11, v11
	v_exp_f32_e32 v180, v180
	v_exp_f32_e32 v181, v181
	v_add_f32_e32 v10, 1.0, v10
	v_add_f32_e32 v11, 1.0, v11
	v_add_f32_e32 v180, 1.0, v180
	v_add_f32_e32 v181, 1.0, v181
	v_rcp_f32_e32 v10, v10
	v_rcp_f32_e32 v11, v11
	v_rcp_f32_e32 v180, v180
	v_rcp_f32_e32 v181, v181
	v_mul_f32_e32 v10, v10, v178
	v_mul_f32_e32 v11, v11, v164
	v_mul_f32_e32 v180, v180, v179
	v_mul_f32_e32 v181, v181, v168
	v_mul_f32_e32 v10, v10, v180
	v_mul_f32_e32 v11, v11, v181
	v_lshlrev_b32_e32 v178, 16, v165
	v_and_b32_e32 v165, 0xffff0000, v165
	v_lshlrev_b32_e32 v179, 16, v169
	v_and_b32_e32 v169, 0xffff0000, v169
	v_mul_f32_e32 v12, 0xbfb8aa3b, v12
	v_mul_f32_e32 v13, 0xbfb8aa3b, v13
	v_mul_f32_e32 v180, 0xbfb8aa3b, v179
	v_mul_f32_e32 v181, 0xbfb8aa3b, v169
	v_exp_f32_e32 v12, v12
	v_exp_f32_e32 v13, v13
	v_exp_f32_e32 v180, v180
	v_exp_f32_e32 v181, v181
	v_add_f32_e32 v12, 1.0, v12
	v_add_f32_e32 v13, 1.0, v13
	v_add_f32_e32 v180, 1.0, v180
	v_add_f32_e32 v181, 1.0, v181
	v_rcp_f32_e32 v12, v12
	v_rcp_f32_e32 v13, v13
	v_rcp_f32_e32 v180, v180
	v_rcp_f32_e32 v181, v181
	v_mul_f32_e32 v12, v12, v178
	v_mul_f32_e32 v13, v13, v165
	v_mul_f32_e32 v180, v180, v179
	v_mul_f32_e32 v181, v181, v169
	v_mul_f32_e32 v12, v12, v180
	v_mul_f32_e32 v13, v13, v181
	v_cvt_pk_bf16_f32 v14, v14, v15
	v_cvt_pk_bf16_f32 v15, v16, v17
	v_cvt_pk_bf16_f32 v16, v10, v11
	v_cvt_pk_bf16_f32 v17, v12, v13
	global_store_dwordx4 v[146:147], v[14:17], off
	s_waitcnt vmcnt(2)
	v_lshlrev_b32_e32 v178, 16, v170
	v_and_b32_e32 v170, 0xffff0000, v170
	v_lshlrev_b32_e32 v179, 16, v174
	v_and_b32_e32 v174, 0xffff0000, v174
	v_mul_f32_e32 v6, 0xbfb8aa3b, v6
	v_mul_f32_e32 v7, 0xbfb8aa3b, v7
	v_mul_f32_e32 v180, 0xbfb8aa3b, v179
	v_mul_f32_e32 v181, 0xbfb8aa3b, v174
	v_exp_f32_e32 v6, v6
	v_exp_f32_e32 v7, v7
	v_exp_f32_e32 v180, v180
	v_exp_f32_e32 v181, v181
	v_add_f32_e32 v6, 1.0, v6
	v_add_f32_e32 v7, 1.0, v7
	v_add_f32_e32 v180, 1.0, v180
	v_add_f32_e32 v181, 1.0, v181
	v_rcp_f32_e32 v6, v6
	v_rcp_f32_e32 v7, v7
	v_rcp_f32_e32 v180, v180
	v_rcp_f32_e32 v181, v181
	v_mul_f32_e32 v6, v6, v178
	v_mul_f32_e32 v7, v7, v170
	v_mul_f32_e32 v180, v180, v179
	v_mul_f32_e32 v181, v181, v174
	v_mul_f32_e32 v6, v6, v180
	v_mul_f32_e32 v7, v7, v181
	v_lshlrev_b32_e32 v178, 16, v171
	v_and_b32_e32 v171, 0xffff0000, v171
	v_lshlrev_b32_e32 v179, 16, v175
	v_and_b32_e32 v175, 0xffff0000, v175
	v_mul_f32_e32 v8, 0xbfb8aa3b, v8
	v_mul_f32_e32 v9, 0xbfb8aa3b, v9
	v_mul_f32_e32 v180, 0xbfb8aa3b, v179
	v_mul_f32_e32 v181, 0xbfb8aa3b, v175
	v_exp_f32_e32 v8, v8
	v_exp_f32_e32 v9, v9
	v_exp_f32_e32 v180, v180
	v_exp_f32_e32 v181, v181
	v_add_f32_e32 v8, 1.0, v8
	v_add_f32_e32 v9, 1.0, v9
	v_add_f32_e32 v180, 1.0, v180
	v_add_f32_e32 v181, 1.0, v181
	v_rcp_f32_e32 v8, v8
	v_rcp_f32_e32 v9, v9
	v_rcp_f32_e32 v180, v180
	v_rcp_f32_e32 v181, v181
	v_mul_f32_e32 v8, v8, v178
	v_mul_f32_e32 v9, v9, v171
	v_mul_f32_e32 v180, v180, v179
	v_mul_f32_e32 v181, v181, v175
	v_mul_f32_e32 v8, v8, v180
	v_mul_f32_e32 v9, v9, v181
	v_lshlrev_b32_e32 v178, 16, v172
	v_and_b32_e32 v172, 0xffff0000, v172
	v_lshlrev_b32_e32 v179, 16, v176
	v_and_b32_e32 v176, 0xffff0000, v176
	v_mul_f32_e32 v2, 0xbfb8aa3b, v2
	v_mul_f32_e32 v3, 0xbfb8aa3b, v3
	v_mul_f32_e32 v180, 0xbfb8aa3b, v179
	v_mul_f32_e32 v181, 0xbfb8aa3b, v176
	v_exp_f32_e32 v2, v2
	v_exp_f32_e32 v3, v3
	v_exp_f32_e32 v180, v180
	v_exp_f32_e32 v181, v181
	v_add_f32_e32 v2, 1.0, v2
	v_add_f32_e32 v3, 1.0, v3
	v_add_f32_e32 v180, 1.0, v180
	v_add_f32_e32 v181, 1.0, v181
	v_rcp_f32_e32 v2, v2
	v_rcp_f32_e32 v3, v3
	v_rcp_f32_e32 v180, v180
	v_rcp_f32_e32 v181, v181
	v_mul_f32_e32 v2, v2, v178
	v_mul_f32_e32 v3, v3, v172
	v_mul_f32_e32 v180, v180, v179
	v_mul_f32_e32 v181, v181, v176
	v_mul_f32_e32 v2, v2, v180
	v_mul_f32_e32 v3, v3, v181
	v_lshlrev_b32_e32 v178, 16, v173
	v_and_b32_e32 v173, 0xffff0000, v173
	v_lshlrev_b32_e32 v179, 16, v177
	v_and_b32_e32 v177, 0xffff0000, v177
	v_mul_f32_e32 v4, 0xbfb8aa3b, v4
	v_mul_f32_e32 v5, 0xbfb8aa3b, v5
	v_mul_f32_e32 v180, 0xbfb8aa3b, v179
	v_mul_f32_e32 v181, 0xbfb8aa3b, v177
	v_exp_f32_e32 v4, v4
	v_exp_f32_e32 v5, v5
	v_exp_f32_e32 v180, v180
	v_exp_f32_e32 v181, v181
	v_add_f32_e32 v4, 1.0, v4
	v_add_f32_e32 v5, 1.0, v5
	v_add_f32_e32 v180, 1.0, v180
	v_add_f32_e32 v181, 1.0, v181
	v_rcp_f32_e32 v4, v4
	v_rcp_f32_e32 v5, v5
	v_rcp_f32_e32 v180, v180
	v_rcp_f32_e32 v181, v181
	v_mul_f32_e32 v4, v4, v178
	v_mul_f32_e32 v5, v5, v173
	v_mul_f32_e32 v180, v180, v179
	v_mul_f32_e32 v181, v181, v177
	v_mul_f32_e32 v4, v4, v180
	v_mul_f32_e32 v5, v5, v181
	v_cvt_pk_bf16_f32 v6, v6, v7
	v_cvt_pk_bf16_f32 v7, v8, v9
	v_cvt_pk_bf16_f32 v8, v2, v3
	v_cvt_pk_bf16_f32 v9, v4, v5
	global_store_dwordx4 v[146:147], v[6:9], off offset:256
	s_andn2_b64 vcc, exec, s[38:39]
	s_mov_b64 s[4:5], -1
	s_cbranch_vccnz .LBB0_686
	s_andn2_b64 vcc, exec, s[42:43]
	s_cbranch_vccnz .LBB0_685
	s_barrier
	s_branch .LBB0_685
	s_nop 0
	s_nop 0
	s_nop 0
	s_nop 0
	s_nop 0
	s_nop 0
	s_nop 0
	s_nop 0
	s_nop 0
	s_nop 0
	s_nop 0
	s_nop 0
	s_nop 0
	s_nop 0
	s_nop 0
	s_nop 0
	s_nop 0
	s_nop 0
	s_nop 0
	s_nop 0
	s_nop 0
	s_nop 0
	s_nop 0
	s_nop 0
	s_nop 0
	s_nop 0
	s_nop 0
	s_nop 0
	s_nop 0
	s_nop 0
	s_nop 0
	s_nop 0
	s_nop 0
	s_nop 0
	s_nop 0
	s_nop 0
	s_nop 0
	s_nop 0
	s_nop 0
	s_nop 0
	s_nop 0
	s_nop 0
	s_nop 0
	s_nop 0
	s_nop 0
	s_nop 0
	s_nop 0
	s_nop 0
	s_nop 0
	s_nop 0
	s_nop 0
	s_nop 0
	s_nop 0
	s_nop 0
	s_nop 0
	s_nop 0
	s_nop 0
	s_nop 0
	s_nop 0
	s_nop 0
	s_nop 0
	s_nop 0
